# P3 attention queue: one static s_setprio 1 for waves 0-3 at P3 entry (reset at exit), the 16 per-cluster priority flips inside P3 deleted
# speedup vs baseline: 1.0138x; 1.0001x over previous
; #define LAS __attribute__((address_space(3)))
; DI int transposes_total(bool late) { int total = 0; for (int s = 0; s < NSEG; ++s) if (seg_late(s) == late) total += (SEGS[s].K / 64) * ((SEGS[s].len + 31) / 32); return total; }
; #define REP_BEGIN(k) for (int rep_ = 0; rep_ < (((PROBE_DBL >> (k)) & 1) ? 2 : 1); ++rep_) {
; __global__ void __launch_bounds__(512) fwd_kernel(Params P) {
;     ...
;     if (IN(3)) { REP_BEGIN(3)
;         volatile LAS int* qs_ = (volatile LAS int*)(L + AL_MISC + 256);
;         bool pp_seen = false;
;         for (;;) {
;             __syncthreads();
;             if (tid == 0) qs_[0] = (int)atomicAdd(CTL + CW_Q3 + REPQ, 1u);
;             __syncthreads();
;             const int u = qs_[0];
;             const int nlate = transposes_total(true), nlate_wg = (nlate + 7) >> 3;
;             if (u >= 128 + 2048 + nlate_wg) break;
.LBB0_462:
	v_readlane_b32 s0, v251, 15
	v_readlane_b32 s1, v251, 16
	s_cmp_lt_i32 s0, 4
	v_readlane_b32 s2, v251, 17
	v_readlane_b32 s3, v251, 18
	s_cselect_b64 s[0:1], -1, 0
	s_and_b64 s[2:3], s[0:1], s[4:5]
	s_andn2_b64 vcc, exec, s[2:3]
	s_cbranch_vccnz .LBB0_820
	v_writelane_b32 v251, s2, 41
	s_getpc_b64 s[0:1]
	s_add_u32 s0, s0, SEGS@rel32@lo+544
	s_addc_u32 s1, s1, SEGS@rel32@hi+552
	v_writelane_b32 v251, s3, 42
	s_getpc_b64 s[2:3]
	s_add_u32 s2, s2, SEGS@rel32@lo+552
	s_addc_u32 s3, s3, SEGS@rel32@hi+560
	s_getpc_b64 s[4:5]
	s_add_u32 s4, s4, SEGS@rel32@lo+592
	s_addc_u32 s5, s5, SEGS@rel32@hi+600
	s_getpc_b64 s[6:7]
	s_add_u32 s6, s6, SEGS@rel32@lo+600
	s_addc_u32 s7, s7, SEGS@rel32@hi+608
	s_getpc_b64 s[8:9]
	s_add_u32 s8, s8, SEGS@rel32@lo+640
	s_addc_u32 s9, s9, SEGS@rel32@hi+648
	s_getpc_b64 s[10:11]
	s_add_u32 s10, s10, SEGS@rel32@lo+648
	s_addc_u32 s11, s11, SEGS@rel32@hi+656
	s_getpc_b64 s[12:13]
	s_add_u32 s12, s12, SEGS@rel32@lo+688
	s_addc_u32 s13, s13, SEGS@rel32@hi+696
	s_getpc_b64 s[14:15]
	s_add_u32 s14, s14, SEGS@rel32@lo+696
	s_addc_u32 s15, s15, SEGS@rel32@hi+704
	s_load_dword s0, s[0:1], 0x0
	s_nop 0
	s_load_dword s16, s[2:3], 0x0
	s_load_dword s1, s[4:5], 0x0
	s_nop 0
	s_load_dword s6, s[6:7], 0x0
	s_nop 0
	s_load_dword s2, s[8:9], 0x0
	s_load_dword s7, s[10:11], 0x0
	s_load_dword s3, s[12:13], 0x0
	s_nop 0
	s_load_dword s8, s[14:15], 0x0
	s_waitcnt lgkmcnt(0)
	s_ashr_i32 s4, s0, 31
	s_lshr_b32 s4, s4, 26
	s_add_i32 s0, s0, s4
	s_add_i32 s4, s16, 31
	s_ashr_i32 s5, s4, 31
	s_lshr_b32 s5, s5, 27
	s_add_i32 s4, s4, s5
	s_ashr_i32 s0, s0, 6
	s_ashr_i32 s4, s4, 5
	s_mul_i32 s64, s4, s0
	s_ashr_i32 s0, s1, 31
	s_lshr_b32 s0, s0, 26
	s_add_i32 s1, s1, s0
	s_ashr_i32 s0, s1, 6
	s_add_i32 s1, s6, 31
	s_ashr_i32 s4, s1, 31
	s_lshr_b32 s4, s4, 27
	s_add_i32 s1, s1, s4
	s_ashr_i32 s1, s1, 5
	s_mul_i32 s65, s1, s0
	s_ashr_i32 s1, s2, 31
	s_lshr_b32 s1, s1, 26
	s_add_i32 s2, s2, s1
	s_ashr_i32 s1, s2, 6
	s_add_i32 s2, s7, 31
	s_ashr_i32 s4, s2, 31
	s_lshr_b32 s4, s4, 27
	s_add_i32 s2, s2, s4
	s_ashr_i32 s2, s2, 5
	s_mul_i32 s74, s2, s1
	s_ashr_i32 s1, s3, 31
	s_lshr_b32 s1, s1, 26
	s_add_i32 s3, s3, s1
	s_add_i32 s2, s8, 31
	s_ashr_i32 s1, s3, 6
	s_ashr_i32 s3, s2, 31
	s_lshr_b32 s3, s3, 27
	s_add_i32 s2, s2, s3
	v_writelane_b32 v251, s96, 43
	s_add_i32 s0, s65, s64
	s_ashr_i32 s2, s2, 5
	v_writelane_b32 v251, s97, 44
	s_add_i32 s0, s0, s74
	s_mul_i32 s75, s2, s1
	v_writelane_b32 v251, s16, 45
	s_add_i32 s16, s0, s75
	s_getpc_b64 s[0:1]
	s_add_u32 s0, s0, SEGS@rel32@lo+736
	s_addc_u32 s1, s1, SEGS@rel32@hi+744
	s_getpc_b64 s[2:3]
	s_add_u32 s2, s2, SEGS@rel32@lo+744
	s_addc_u32 s3, s3, SEGS@rel32@hi+752
	v_writelane_b32 v251, s6, 46
	s_getpc_b64 s[4:5]
	s_add_u32 s4, s4, SEGS@rel32@lo+880
	s_addc_u32 s5, s5, SEGS@rel32@hi+888
	v_writelane_b32 v251, s7, 47
	s_getpc_b64 s[6:7]
	s_add_u32 s6, s6, SEGS@rel32@lo+888
	s_addc_u32 s7, s7, SEGS@rel32@hi+896
	v_writelane_b32 v251, s8, 48
	s_getpc_b64 s[8:9]
	s_add_u32 s8, s8, SEGS@rel32@lo+928
	s_addc_u32 s9, s9, SEGS@rel32@hi+936
	s_getpc_b64 s[10:11]
	s_add_u32 s10, s10, SEGS@rel32@lo+936
	s_addc_u32 s11, s11, SEGS@rel32@hi+944
	s_getpc_b64 s[12:13]
	s_add_u32 s12, s12, SEGS@rel32@lo+976
	s_addc_u32 s13, s13, SEGS@rel32@hi+984
	s_getpc_b64 s[14:15]
	s_add_u32 s14, s14, SEGS@rel32@lo+984
	s_addc_u32 s15, s15, SEGS@rel32@hi+992
	s_load_dword s0, s[0:1], 0x0
	s_nop 0
	s_load_dword s17, s[2:3], 0x0
	s_load_dword s1, s[4:5], 0x0
	s_nop 0
	s_load_dword s6, s[6:7], 0x0
	s_nop 0
	s_load_dword s2, s[8:9], 0x0
	s_load_dword s7, s[10:11], 0x0
	s_load_dword s3, s[12:13], 0x0
	s_nop 0
	s_load_dword s8, s[14:15], 0x0
	s_waitcnt lgkmcnt(0)
	s_ashr_i32 s4, s0, 31
	s_lshr_b32 s4, s4, 26
	s_add_i32 s0, s0, s4
	s_add_i32 s4, s17, 31
	s_ashr_i32 s5, s4, 31
	s_lshr_b32 s5, s5, 27
	s_add_i32 s4, s4, s5
	s_ashr_i32 s0, s0, 6
	s_ashr_i32 s4, s4, 5
	s_mul_i32 s81, s4, s0
	s_ashr_i32 s4, s1, 31
	s_lshr_b32 s4, s4, 26
	s_add_i32 s1, s1, s4
	s_add_i32 s4, s6, 31
	s_ashr_i32 s5, s4, 31
	s_lshr_b32 s5, s5, 27
	s_add_i32 s4, s4, s5
	s_ashr_i32 s1, s1, 6
	s_ashr_i32 s4, s4, 5
	s_mul_i32 s91, s4, s1
	s_ashr_i32 s1, s2, 31
	s_lshr_b32 s1, s1, 26
	s_add_i32 s2, s2, s1
	s_ashr_i32 s1, s2, 6
	s_add_i32 s2, s7, 31
	s_ashr_i32 s4, s2, 31
	s_lshr_b32 s4, s4, 27
	s_add_i32 s2, s2, s4
	s_ashr_i32 s2, s2, 5
	s_mul_i32 s92, s2, s1
	s_ashr_i32 s1, s3, 31
	s_lshr_b32 s1, s1, 26
	s_add_i32 s3, s3, s1
	s_add_i32 s2, s8, 31
	s_ashr_i32 s1, s3, 6
	s_ashr_i32 s3, s2, 31
	s_lshr_b32 s3, s3, 27
	s_add_i32 s0, s16, s81
	s_add_i32 s2, s2, s3
	s_add_i32 s0, s0, s91
	s_ashr_i32 s2, s2, 5
	s_add_i32 s0, s0, s92
	s_mul_i32 s87, s2, s1
	s_add_i32 s12, s0, s87
	s_getpc_b64 s[0:1]
	s_add_u32 s0, s0, SEGS@rel32@lo+1024
	s_addc_u32 s1, s1, SEGS@rel32@hi+1032
	v_writelane_b32 v251, s17, 49
	s_getpc_b64 s[2:3]
	s_add_u32 s2, s2, SEGS@rel32@lo+1032
	s_addc_u32 s3, s3, SEGS@rel32@hi+1040
	v_writelane_b32 v251, s6, 50
	s_getpc_b64 s[4:5]
	s_add_u32 s4, s4, SEGS@rel32@lo+1072
	s_addc_u32 s5, s5, SEGS@rel32@hi+1080
	v_writelane_b32 v251, s7, 51
	s_getpc_b64 s[6:7]
	s_add_u32 s6, s6, SEGS@rel32@lo+1080
	s_addc_u32 s7, s7, SEGS@rel32@hi+1088
	v_writelane_b32 v251, s8, 52
	s_getpc_b64 s[8:9]
	s_add_u32 s8, s8, SEGS@rel32@lo+1120
	s_addc_u32 s9, s9, SEGS@rel32@hi+1128
	s_getpc_b64 s[10:11]
	s_add_u32 s10, s10, SEGS@rel32@lo+1128
	s_addc_u32 s11, s11, SEGS@rel32@hi+1136
	s_load_dword s0, s[0:1], 0x0
	s_nop 0
	s_load_dword s13, s[2:3], 0x0
	s_load_dword s1, s[4:5], 0x0
	s_nop 0
	s_load_dword s5, s[6:7], 0x0
	s_load_dword s2, s[8:9], 0x0
	s_nop 0
	s_load_dword s6, s[10:11], 0x0
	s_waitcnt lgkmcnt(0)
; DI int transposes_total(bool late) { int total = 0; for (int s = 0; s < NSEG; ++s) if (seg_late(s) == late) total += (SEGS[s].K / 64) * ((SEGS[s].len + 31) / 32); return total; }
; __global__ void __launch_bounds__(512) fwd_kernel(Params P) {
;     ...
;             const int nlate = transposes_total(true), nlate_wg = (nlate + 7) >> 3;
;             if (u >= 128 + 2048 + nlate_wg) break;
	s_ashr_i32 s3, s0, 31
	s_lshr_b32 s3, s3, 26
	s_add_i32 s0, s0, s3
	s_add_i32 s3, s13, 31
	s_ashr_i32 s4, s3, 31
	s_lshr_b32 s4, s4, 27
	s_add_i32 s3, s3, s4
	s_ashr_i32 s0, s0, 6
	s_ashr_i32 s3, s3, 5
	s_mul_i32 s88, s3, s0
	s_ashr_i32 s3, s1, 31
	s_lshr_b32 s3, s3, 26
	s_add_i32 s1, s1, s3
	s_add_i32 s3, s5, 31
	s_ashr_i32 s4, s3, 31
	s_lshr_b32 s4, s4, 27
	s_add_i32 s3, s3, s4
	s_ashr_i32 s1, s1, 6
	s_ashr_i32 s3, s3, 5
	s_mul_i32 s89, s3, s1
	s_ashr_i32 s1, s2, 31
	s_lshr_b32 s1, s1, 26
	s_add_i32 s2, s2, s1
	s_ashr_i32 s1, s2, 6
	s_add_i32 s2, s6, 31
	s_ashr_i32 s3, s2, 31
	s_lshr_b32 s3, s3, 27
	s_add_i32 s2, s2, s3
	v_writelane_b32 v251, s13, 53
	s_add_i32 s0, s12, s88
	s_ashr_i32 s2, s2, 5
	v_writelane_b32 v251, s5, 54
	s_add_i32 s0, s0, s89
	s_mul_i32 s2, s2, s1
	v_writelane_b32 v251, s6, 55
	s_add_i32 s0, s0, s2
	v_writelane_b32 v251, s0, 56
	s_add_i32 s0, s0, 7
	s_ashr_i32 s0, s0, 3
	s_addk_i32 s0, 0x880
	v_writelane_b32 v251, s0, 57
	s_add_u32 s0, s34, 0x7800000
	s_addc_u32 s1, s35, 0
	v_writelane_b32 v251, s0, 58
	v_lshrrev_b32_e32 v3, 3, v194
	v_lshlrev_b32_e32 v0, 3, v194
	v_writelane_b32 v251, s1, 59
	s_add_u32 s0, s34, 0xfd00000
	v_writelane_b32 v251, s0, 60
	s_addc_u32 s0, s35, 0
	v_writelane_b32 v251, s0, 61
	s_add_u32 s0, s34, 0x3100000
	v_writelane_b32 v251, s0, 62
	s_addc_u32 s0, s35, 0
	s_lshl_b32 s1, s90, 5
	s_add_u32 s2, s34, 0x3210000
	s_addc_u32 s3, s35, 0
	s_add_u32 s4, s34, 0x3300000
	v_lshlrev_b32_e32 v4, 4, v194
	s_addc_u32 s5, s35, 0
	v_and_b32_e32 v130, 56, v0
	v_mul_u32_u24_e32 v0, 0x90, v3
	v_and_b32_e32 v4, 0x70, v4
	s_add_u32 s6, s34, 0x14200000
	v_add3_u32 v127, 0, v0, v4
	v_lshlrev_b32_e32 v4, 1, v194
	v_lshrrev_b32_e32 v5, 1, v192
	s_addc_u32 s7, s35, 0
	v_and_b32_e32 v0, 19, v194
	v_and_b32_e32 v4, 8, v4
	v_and_b32_e32 v6, 4, v5
	v_writelane_b32 v250, s6, 0
	v_writelane_b32 v251, s0, 63
	v_or3_b32 v0, v4, v0, v6
	v_writelane_b32 v250, s7, 1
	s_bfe_u32 s0, s30, 0x20006
	v_mov_b32_e32 v1, 0
	v_mul_u32_u24_e32 v131, 0x90, v0
	v_writelane_b32 v250, s0, 2
	v_lshlrev_b32_e32 v0, 7, v3
	v_and_b32_e32 v122, 31, v194
	v_and_b32_e32 v133, 16, v5
	s_lshl_b32 s0, s90, 3
	v_writelane_b32 v250, s2, 3
	v_lshlrev_b32_e32 v6, 1, v130
	v_mov_b32_e32 v7, v1
	v_lshl_add_u64 v[4:5], s[2:3], 0, v[0:1]
	v_mul_u32_u24_e32 v128, 0x840, v3
	v_mul_u32_u24_e32 v132, 0x4040, v3
	s_mov_b32 s93, s0
	s_and_b32 s7, s0, 0x1fffffe0
	v_lshl_add_u64 v[136:137], v[4:5], 0, v[6:7]
	v_lshlrev_b32_e32 v4, 11, v3
	s_add_i32 s0, 0, 0x1a544
	v_lshlrev_b32_e32 v3, 2, v122
	v_writelane_b32 v250, s3, 4
	v_add_u32_e32 v171, s0, v3
	s_add_i32 s0, 0, 0x19904
	v_writelane_b32 v250, s4, 5
	s_add_u32 s2, s34, 0x3200000
	s_addc_u32 s3, s35, 0
	v_writelane_b32 v250, s5, 6
	v_lshlrev_b32_e32 v10, 2, v194
	v_or_b32_e32 v179, s7, v122
	v_writelane_b32 v250, s2, 7
	v_add_u32_e32 v180, s0, v10
	v_lshl_add_u32 v186, v179, 5, s0
	v_writelane_b32 v250, s3, 8
	s_add_i32 s0, s90, 0xffffbc00
	v_writelane_b32 v250, s0, 9
	s_mul_i32 s0, s90, 0x2100
	v_readlane_b32 s8, v251, 4
	v_mov_b32_e32 v5, v1
	s_add_i32 s0, s0, 0
	v_readlane_b32 s10, v251, 6
	v_readlane_b32 s11, v251, 7
	v_lshrrev_b32_e32 v124, 5, v192
	v_lshl_add_u64 v[8:9], s[4:5], 0, v[4:5]
	s_movk_i32 s6, 0x104
	v_mov_b32_e32 v5, 0x8200
	s_cmp_lg_u64 s[10:11], 0
	v_lshlrev_b32_e32 v126, 3, v124
	v_lshl_add_u64 v[138:139], v[8:9], 0, v[6:7]
	v_lshlrev_b64 v[6:7], v192, -1
	v_mad_u32_u24 v177, v192, s6, v5
	v_and_b32_e32 v5, 7, v194
	s_cselect_b64 s[2:3], -1, 0
	v_or_b32_e32 v9, s1, v122
	v_not_b32_e32 v140, v6
	v_lshlrev_b32_e64 v6, v194, -1
	v_writelane_b32 v250, s2, 10
	v_lshrrev_b32_e32 v188, 3, v192
	v_sub_u32_e32 v195, v9, v126
	v_lshlrev_b32_e32 v9, 4, v5
	v_lshl_add_u32 v181, v5, 2, 0
	v_not_b32_e32 v185, v6
	v_writelane_b32 v250, s3, 11
	v_mul_u32_u24_e32 v6, 0x84, v130
	v_lshlrev_b32_e32 v8, 2, v188
	v_or_b32_e32 v4, v4, v9
	v_mov_b32_e32 v5, v1
	v_add_u32_e32 v3, s0, v3
; #define LAS __attribute__((address_space(3)))
; __global__ void __launch_bounds__(512) fwd_kernel(Params P) {
;     ...
;         volatile LAS int* qs_ = (volatile LAS int*)(L + AL_MISC + 256);
;         bool pp_seen = false;
;         for (;;) {
;             __syncthreads();
;             if (tid == 0) qs_[0] = (int)atomicAdd(CTL + CW_Q3 + REPQ, 1u);
;             __syncthreads();
;             const int u = qs_[0];
	v_add3_u32 v189, s0, v6, v8
	v_writelane_b32 v250, s1, 12
	v_lshl_add_u64 v[4:5], s[34:35], 0, v[4:5]
	s_mov_b64 s[0:1], 0x3300080
	v_or_b32_e32 v0, v0, v9
	v_lshl_add_u64 v[142:143], v[4:5], 0, s[0:1]
	v_lshl_add_u64 v[4:5], s[34:35], 0, v[0:1]
	s_mov_b64 s[0:1], 0x3212000
	v_lshl_add_u64 v[144:145], v[4:5], 0, s[0:1]
	s_movk_i32 s0, 0x100
	v_writelane_b32 v250, s7, 13
	v_cmp_gt_u32_e64 s[0:1], s0, v194
	s_cmp_eq_u64 s[38:39], 0
	v_sub_u32_e32 v0, v126, v122
	v_writelane_b32 v250, s0, 14
	v_readlane_b32 s14, v251, 10
	v_readlane_b32 s15, v251, 11
	v_writelane_b32 v250, s1, 15
	s_cselect_b64 s[0:1], -1, 0
	v_writelane_b32 v250, s0, 16
	v_subrev_u32_e32 v201, s7, v0
	v_lshlrev_b32_e32 v0, 2, v192
	v_writelane_b32 v250, s1, 17
	s_add_i32 s0, 0, 0x9200
	v_writelane_b32 v250, s0, 18
	v_cmp_gt_u32_e64 s[0:1], 64, v194
	v_lshlrev_b32_e32 v2, 6, v194
	v_add_u32_e32 v129, 0, v10
	v_writelane_b32 v250, s0, 19
	v_mul_u32_u24_e32 v135, 0x90, v122
	v_not_b32_e32 v123, v7
	v_writelane_b32 v250, s1, 20
	v_cmp_lt_u32_e64 s[0:1], 31, v192
	v_lshrrev_b32_e32 v182, 5, v194
	v_readlane_b32 s9, v251, 5
	v_writelane_b32 v250, s0, 21
	v_readlane_b32 s12, v251, 8
	v_readlane_b32 s13, v251, 9
	v_writelane_b32 v250, s1, 22
	v_cmp_ne_u32_e64 s[0:1], 0, v192
	v_mul_u32_u24_e32 v7, 0x84, v124
	v_or_b32_e32 v6, 0x3c0, v194
	v_writelane_b32 v250, s0, 23
	v_or_b32_e32 v8, 0x7c0, v194
	v_or_b32_e32 v10, 0xbc0, v194
	v_writelane_b32 v250, s1, 24
	v_cmp_gt_u32_e64 s[0:1], 16, v194
	v_or_b32_e32 v12, 0xfc0, v194
	v_lshl_add_u64 v[146:147], s[34:35], 0, v[0:1]
	v_writelane_b32 v250, s0, 25
	s_mov_b32 s18, 0x41b00000
	s_mov_b32 s4, 0x42580000
	v_writelane_b32 v250, s1, 26
	v_cmp_lt_u32_e64 s[0:1], 31, v194
	s_mov_b32 s14, 0x42500000
	s_mov_b32 s16, 0x42480000
	v_writelane_b32 v250, s0, 27
	s_mov_b32 s94, 0x42400000
	s_mov_b32 s96, 0x42180000
	v_writelane_b32 v250, s1, 28
	s_mov_b64 s[0:1], 0
	v_writelane_b32 v250, s0, 29
	s_mov_b32 s84, 0x42100000
	s_mov_b32 s72, 0x42080000
	v_writelane_b32 v250, s1, 30
	v_writelane_b32 v250, s87, 31
	s_mov_b32 s44, 0x42000000
	v_mbcnt_lo_u32_b32 v0, -1, 0
	v_writelane_b32 v250, s88, 32
	v_lshlrev_b32_e32 v141, 4, v124
	v_lshlrev_b32_e32 v134, 2, v124
	v_add3_u32 v170, 0, v131, v133
	v_add3_u32 v172, 0, v135, v133
	v_lshlrev_b32_e32 v173, 8, v124
	v_mul_u32_u24_e32 v174, 0x104, v192
	v_or_b32_e32 v175, 64, v192
	v_or_b32_e32 v176, 0x80, v192
	v_or_b32_e32 v178, 0xc0, v192
	v_lshl_add_u32 v183, v182, 2, 0
	v_lshlrev_b32_e64 v184, v194, 1
	v_lshlrev_b32_e32 v187, 10, v192
	v_or_b32_e32 v190, 8, v188
	v_or_b32_e32 v191, 16, v188
	v_or_b32_e32 v193, 24, v188
	v_mov_b32_e32 v125, v1
	v_sub_u32_e32 v196, 0, v126
	v_lshl_or_b32 v197, v124, 7, 31
	v_add_u32_e32 v198, 0x9400, v129
	v_add_u32_e32 v199, 0xfffffe00, v194
	v_sub_u32_e32 v200, v179, v126
	v_mov_b32_e32 v202, 0x260
	v_lshlrev_b32_e32 v203, 2, v2
	s_mov_b32 s19, 0x41b80000
	s_mov_b32 s5, 0x425c0000
	s_mov_b32 s15, 0x42540000
	s_mov_b32 s17, 0x424c0000
	s_mov_b32 s95, 0x42440000
	s_mov_b32 s97, 0x421c0000
	s_mov_b32 s85, 0x42140000
	s_mov_b32 s73, 0x420c0000
	s_mov_b32 s45, 0x42040000
	v_lshlrev_b32_e32 v148, 2, v192
	v_lshlrev_b32_e32 v204, 2, v6
	v_lshlrev_b32_e32 v205, 2, v8
	v_lshlrev_b32_e32 v206, 2, v10
	v_lshlrev_b32_e32 v207, 2, v12
	v_mov_b32_e32 v208, 0x1080
	v_mbcnt_hi_u32_b32 v209, -1, v0
	v_mov_b32_e32 v210, 0xf149f2ca
	v_mov_b32_e32 v211, 0x42800000
	v_mov_b32_e32 v212, 0x44
	v_mov_b32_e32 v213, 0x80
	v_add_u32_e32 v214, v3, v7
	s_movk_i32 s10, 0x200
	s_movk_i32 s11, 0x220
	s_movk_i32 s76, 0x21f
	s_movk_i32 s77, 0x23f
	s_mov_b32 s83, 0
	v_cmp_gt_u32_e64 s[8:9], 32, v192
	v_cmp_eq_u32_e64 s[12:13], 0, v192
	s_mov_b32 s80, 0xbfb8aa3b
	v_writelane_b32 v250, s89, 33
	v_writelane_b32 v250, s75, 34
	v_readfirstlane_b32 s0, v194
	s_lshr_b32 s0, s0, 6
	s_cmp_ge_u32 s0, 4
	s_cbranch_scc1 .Lp3_prio_done
	s_setprio 1
.Lp3_prio_done:
	s_mov_b32 s98, 0
	s_branch .LBB0_468

; DI void qk_acc(lptr Kt, const bf16x8 (&qf)[4], f32x16& s0, f32x16& s1, int lane) {
;     const int i = lane & 31, hi = lane >> 5;
;     const int krow = (i & 19) | ((i & 4) << 1) | ((i & 8) >> 1);
;     lptr kp = Kt + krow * KPB + hi * 16;
;     bf16x8 a0[4], a1[4];
; #pragma unroll
;     for (int d0 = 0; d0 < 4; ++d0) { a0[d0] = *(LAS bf16x8*)(kp + d0 * 32); a1[d0] = *(LAS bf16x8*)(kp + 32 * KPB + d0 * 32); }
;     __builtin_amdgcn_s_setprio(1);
; template <int MODE>
; DI void bias_init(f32x16& s0, f32x16& s1, const TP& tp, float fbm, int hi) {
; #pragma unroll
;     for (int r = 0; r < 16; ++r) {
;         const int kvc = 16 * (r >> 3) + (r & 7);
;         if (MODE == 0) { s0[r] = __builtin_fmaf(-L2E, tp.cs[kvc + 8 * hi], fbm); s1[r] = __builtin_fmaf(-L2E, tp.cs[kvc + 32 + 8 * hi], fbm); }
;         else { s0[r] = __builtin_fmaf(tp.sl, (float)kvc, fbm); s1[r] = __builtin_fmaf(tp.sl, (float)(kvc + 32), fbm); }
;     }
; }
; DI float max3_asm(float a, float b, float c) { float r; asm("v_max3_f32 %0, %1, %2, %3" : "=v"(r) : "v"(a), "v"(b), "v"(c)); return r; }
; template <bool MASK>
; DI float mask_rowmax(f32x16& s0, f32x16& s1, const TP& tp) {
;     if (MASK) {
; #pragma unroll
;         for (int r = 0; r < 16; ++r) {
;             const int kvc = 16 * (r >> 3) + (r & 7);
;             const bool v0 = tp.sel && (kvc <= tp.lim) && (kvc > tp.lim2), v1 = tp.sel && (kvc + 32 <= tp.lim) && (kvc + 32 > tp.lim2);
;             s0[r] = v0 ? s0[r] : -1e30f; s1[r] = v1 ? s1[r] : -1e30f;
;         }
;     }
;     const float seed = __builtin_fminf(s0[15], s1[15]);
;     float ma = seed, mb = seed;
; #pragma unroll
;     for (int r = 0; r < 16; r += 2) { ma = max3_asm(ma, s0[r], s1[r]); mb = max3_asm(mb, s0[r + 1], s1[r + 1]); }
;     const float mx = fmaxf(ma, mb);
;     return fmaxf(mx, __shfl_xor(mx, 32));
; }
; template <int MODE, bool MASK, bool WITH_O>
; DI void attn_tile_t(lptr Kt, lptr Vt, const bf16x8 (&qf)[4], f32x16& o0, f32x16& o1, RowState& rs, const TP& tp, int lane) {
;     const int hi = lane >> 5;
;     f32x16 s0, s1;
;     bias_init<MODE>(s0, s1, tp, tp.fb - rs.mref, hi);
;     qk_acc(Kt, qf, s0, s1, lane);
;     const float mx = mask_rowmax<MASK>(s0, s1, tp);
;     const bool was = rs.seen; rs.seen = was || (mx > -1e29f);
;     const bool trig = (mx > 8.f) || (!was && mx > -1e29f && mx < -8.f);
;     if (__builtin_expect(__any(trig), 0)) {
.LBB0_493:
	s_lshl_b32 s2, s55, 8
	s_add_i32 s26, s2, 0
	s_mul_i32 s2, s55, 0x2300
	s_add_i32 s56, s26, s2
	s_mov_b64 s[2:3], -1
	s_cmp_le_i32 s31, s42
	v_sub_f32_e32 v156, v157, v160
	v_add3_u32 v161, s56, v131, v133
	v_lshl_add_u32 v162, v126, 2, s26
	s_cbranch_scc0 .LBB0_498
	ds_read_b128 v[34:37], v162 offset:36992
	ds_read_b128 v[38:41], v162 offset:36864
	ds_read_b128 v[42:45], v162 offset:36880
	ds_read_b128 v[46:49], v162 offset:37008
	ds_read_b128 v[50:53], v162 offset:36928
	ds_read_b128 v[54:57], v162 offset:37056
	ds_read_b128 v[58:61], v162 offset:36944
	ds_read_b128 v[62:65], v162 offset:37072
	ds_read_b128 v[166:169], v161 offset:4608
	ds_read_b128 v[216:219], v161
	ds_read_b128 v[228:231], v161 offset:32
	ds_read_b128 v[232:235], v161 offset:4640
	ds_read_b128 v[236:239], v161 offset:64
	ds_read_b128 v[240:243], v161 offset:4672
	ds_read_b128 v[244:247], v161 offset:96
	ds_read_b128 v[252:255], v161 offset:4704
	s_waitcnt lgkmcnt(13)
	v_pk_fma_f32 v[88:89], v[44:45], s[80:81], v[156:157] op_sel_hi:[1,0,0]
	s_waitcnt lgkmcnt(11)
	v_pk_fma_f32 v[92:93], v[52:53], s[80:81], v[156:157] op_sel_hi:[1,0,0]
	v_pk_fma_f32 v[84:85], v[40:41], s[80:81], v[156:157] op_sel_hi:[1,0,0]
	s_waitcnt lgkmcnt(9)
	v_pk_fma_f32 v[96:97], v[60:61], s[80:81], v[156:157] op_sel_hi:[1,0,0]
	v_pk_fma_f32 v[94:95], v[58:59], s[80:81], v[156:157] op_sel_hi:[1,0,0]
	v_pk_fma_f32 v[90:91], v[50:51], s[80:81], v[156:157] op_sel_hi:[1,0,0]
	v_pk_fma_f32 v[86:87], v[42:43], s[80:81], v[156:157] op_sel_hi:[1,0,0]
	v_pk_fma_f32 v[82:83], v[38:39], s[80:81], v[156:157] op_sel_hi:[1,0,0]
	s_waitcnt lgkmcnt(8)
	v_pk_fma_f32 v[80:81], v[64:65], s[80:81], v[156:157] op_sel_hi:[1,0,0]
	v_pk_fma_f32 v[76:77], v[56:57], s[80:81], v[156:157] op_sel_hi:[1,0,0]
	v_pk_fma_f32 v[72:73], v[48:49], s[80:81], v[156:157] op_sel_hi:[1,0,0]
	v_pk_fma_f32 v[68:69], v[36:37], s[80:81], v[156:157] op_sel_hi:[1,0,0]
	v_pk_fma_f32 v[78:79], v[62:63], s[80:81], v[156:157] op_sel_hi:[1,0,0]
	v_pk_fma_f32 v[74:75], v[54:55], s[80:81], v[156:157] op_sel_hi:[1,0,0]
	v_pk_fma_f32 v[70:71], v[46:47], s[80:81], v[156:157] op_sel_hi:[1,0,0]
	v_pk_fma_f32 v[66:67], v[34:35], s[80:81], v[156:157] op_sel_hi:[1,0,0]
	s_waitcnt lgkmcnt(6)
	v_mfma_f32_32x32x16_bf16 v[82:97], v[216:219], v[98:101], v[82:97]
	v_mfma_f32_32x32x16_bf16 v[66:81], v[166:169], v[98:101], v[66:81]
	s_waitcnt lgkmcnt(5)
	v_mfma_f32_32x32x16_bf16 v[82:97], v[228:231], v[102:105], v[82:97]
	s_waitcnt lgkmcnt(4)
	v_mfma_f32_32x32x16_bf16 v[66:81], v[232:235], v[102:105], v[66:81]
	s_waitcnt lgkmcnt(3)
	v_mfma_f32_32x32x16_bf16 v[82:97], v[236:239], v[106:109], v[82:97]
	s_waitcnt lgkmcnt(2)
	v_mfma_f32_32x32x16_bf16 v[66:81], v[240:243], v[106:109], v[66:81]
	s_waitcnt lgkmcnt(1)
	v_mfma_f32_32x32x16_bf16 v[82:97], v[244:247], v[110:113], v[82:97]
	s_waitcnt lgkmcnt(0)
	v_mfma_f32_32x32x16_bf16 v[66:81], v[252:255], v[110:113], v[66:81]
	v_add3_u32 v228, s56, v135, v141
	ds_read_b128 v[216:219], v228 offset:18432
	ds_read_b128 v[38:41], v228 offset:23040
	ds_read_b128 v[42:45], v228 offset:18464
	ds_read_b128 v[46:49], v228 offset:23072
	ds_read_b128 v[50:53], v228 offset:18496
	ds_read_b128 v[54:57], v228 offset:23104
	ds_read_b128 v[58:61], v228 offset:18528
	ds_read_b128 v[62:65], v228 offset:23136
	s_nop 1
	v_max_f32_e32 v34, v81, v81
	v_max_f32_e32 v35, v97, v97
	v_min_f32_e32 v34, v35, v34
	v_max3_f32 v35, v34, v82, v66
	v_max3_f32 v34, v34, v83, v67
	v_and_b32_e32 v36, 64, v209
	v_max3_f32 v35, v35, v84, v68
	v_max3_f32 v34, v34, v85, v69
	v_add_u32_e32 v36, 64, v36
	v_max3_f32 v35, v35, v86, v70
	v_max3_f32 v34, v34, v87, v71
	s_mov_b32 s2, 0xefa18f08
	v_max3_f32 v35, v35, v88, v72
	v_max3_f32 v34, v34, v89, v73
	s_mov_b64 s[28:29], -1
	v_max3_f32 v35, v35, v90, v74
	v_max3_f32 v34, v34, v91, v75
	v_max3_f32 v35, v35, v92, v76
	v_max3_f32 v34, v34, v93, v77
	v_max3_f32 v35, v35, v94, v78
	v_max3_f32 v34, v34, v95, v79
	v_max3_f32 v35, v35, v96, v80
	v_max3_f32 v34, v34, v97, v81
	v_max_f32_e32 v34, v34, v34
	v_max_f32_e32 v35, v35, v35
	v_max_f32_e32 v34, v35, v34
	v_mov_b32_e32 v35, v34
	s_nop 1
	v_permlane32_swap_b32_e32 v35, v34
	s_waitcnt lgkmcnt(0)
	v_max_f32_e32 v165, v34, v35
	v_cmp_lt_f32_e64 s[26:27], s2, v165
	s_mov_b32 s2, 0x41000000
	v_cmp_lt_f32_e32 vcc, s2, v165
	s_mov_b32 s28, 0xc1000000
	v_cmp_gt_f32_e64 s[28:29], s28, v165
	s_and_b64 s[28:29], s[28:29], s[26:27]
	s_andn2_b64 s[28:29], s[28:29], s[22:23]
	s_or_b64 s[28:29], s[28:29], vcc
	s_and_b64 vcc, exec, s[28:29]
	v_mov_b32_e32 v163, v160
	v_mov_b32_e32 v164, v159
	s_cbranch_vccnz .LBB0_514

; #define LAS __attribute__((address_space(3)))
; #define MFMA32(a, b, c) __builtin_amdgcn_mfma_f32_32x32x16_bf16((a), (b), (c), 0, 0, 0)
; DI float max3_asm(float a, float b, float c) { float r; asm("v_max3_f32 %0, %1, %2, %3" : "=v"(r) : "v"(a), "v"(b), "v"(c)); return r; }
; DI void qk_acc(lptr Kt, const bf16x8 (&qf)[4], f32x16& s0, f32x16& s1, int lane) {
;     const int i = lane & 31, hi = lane >> 5;
;     const int krow = (i & 19) | ((i & 4) << 1) | ((i & 8) >> 1);
;     lptr kp = Kt + krow * KPB + hi * 16;
;     bf16x8 a0[4], a1[4];
; #pragma unroll
;     for (int d0 = 0; d0 < 4; ++d0) { a0[d0] = *(LAS bf16x8*)(kp + d0 * 32); a1[d0] = *(LAS bf16x8*)(kp + 32 * KPB + d0 * 32); }
;     __builtin_amdgcn_s_setprio(1);
; #pragma unroll
;     for (int d0 = 0; d0 < 4; ++d0) { s0 = MFMA32(a0[d0], qf[d0], s0); s1 = MFMA32(a1[d0], qf[d0], s1); }
;     __builtin_amdgcn_s_setprio(0);
; template <bool MASK>
; DI float mask_rowmax(f32x16& s0, f32x16& s1, const TP& tp) {
;     if (MASK) {
; #pragma unroll
;         for (int r = 0; r < 16; ++r) {
;             const int kvc = 16 * (r >> 3) + (r & 7);
;             const bool v0 = tp.sel && (kvc <= tp.lim) && (kvc > tp.lim2), v1 = tp.sel && (kvc + 32 <= tp.lim) && (kvc + 32 > tp.lim2);
;             s0[r] = v0 ? s0[r] : -1e30f; s1[r] = v1 ? s1[r] : -1e30f;
;         }
;     }
;     const float seed = __builtin_fminf(s0[15], s1[15]);
;     float ma = seed, mb = seed;
; #pragma unroll
;     for (int r = 0; r < 16; r += 2) { ma = max3_asm(ma, s0[r], s1[r]); mb = max3_asm(mb, s0[r + 1], s1[r + 1]); }
;     const float mx = fmaxf(ma, mb);
;     return fmaxf(mx, __shfl_xor(mx, 32));
; }
; template <int MODE, bool MASK, bool WITH_O>
; DI void attn_tile_t(lptr Kt, lptr Vt, const bf16x8 (&qf)[4], f32x16& o0, f32x16& o1, RowState& rs, const TP& tp, int lane) {
;     const int hi = lane >> 5;
;     f32x16 s0, s1;
;     bias_init<MODE>(s0, s1, tp, tp.fb - rs.mref, hi);
;     qk_acc(Kt, qf, s0, s1, lane);
;     const float mx = mask_rowmax<MASK>(s0, s1, tp);
;     const bool was = rs.seen; rs.seen = was || (mx > -1e29f);
;     const bool trig = (mx > 8.f) || (!was && mx > -1e29f && mx < -8.f);
;     if (__builtin_expect(__any(trig), 0)) {
.LBB0_498:
	s_and_b64 vcc, exec, s[2:3]
	s_cbranch_vccz .LBB0_503
	s_nop 8
	ds_read_b128 v[50:53], v162 offset:36992
	ds_read_b128 v[34:37], v162 offset:36864
	ds_read_b128 v[38:41], v162 offset:36880
	ds_read_b128 v[54:57], v162 offset:37008
	ds_read_b128 v[42:45], v162 offset:36928
	ds_read_b128 v[58:61], v162 offset:37056
	ds_read_b128 v[46:49], v162 offset:36944
	ds_read_b128 v[62:65], v162 offset:37072
	ds_read_b128 v[66:69], v161 offset:4608
	ds_read_b128 v[70:73], v161
	ds_read_b128 v[74:77], v161 offset:32
	ds_read_b128 v[78:81], v161 offset:4640
	ds_read_b128 v[82:85], v161 offset:64
	ds_read_b128 v[86:89], v161 offset:4672
	ds_read_b128 v[90:93], v161 offset:96
	ds_read_b128 v[94:97], v161 offset:4704
	s_waitcnt lgkmcnt(11)
	v_pk_fma_f32 v[44:45], v[44:45], s[80:81], v[156:157] op_sel_hi:[1,0,0]
	v_pk_fma_f32 v[40:41], v[40:41], s[80:81], v[156:157] op_sel_hi:[1,0,0]
	v_pk_fma_f32 v[36:37], v[36:37], s[80:81], v[156:157] op_sel_hi:[1,0,0]
	s_waitcnt lgkmcnt(9)
	v_pk_fma_f32 v[46:47], v[46:47], s[80:81], v[156:157] op_sel_hi:[1,0,0]
	v_pk_fma_f32 v[42:43], v[42:43], s[80:81], v[156:157] op_sel_hi:[1,0,0]
	v_pk_fma_f32 v[38:39], v[38:39], s[80:81], v[156:157] op_sel_hi:[1,0,0]
	v_pk_fma_f32 v[34:35], v[34:35], s[80:81], v[156:157] op_sel_hi:[1,0,0]
	v_pk_fma_f32 v[56:57], v[56:57], s[80:81], v[156:157] op_sel_hi:[1,0,0]
	v_pk_fma_f32 v[52:53], v[52:53], s[80:81], v[156:157] op_sel_hi:[1,0,0]
	v_pk_fma_f32 v[54:55], v[54:55], s[80:81], v[156:157] op_sel_hi:[1,0,0]
	v_pk_fma_f32 v[50:51], v[50:51], s[80:81], v[156:157] op_sel_hi:[1,0,0]
	v_pk_fma_f32 v[48:49], v[48:49], s[80:81], v[156:157] op_sel_hi:[1,0,0]
	s_waitcnt lgkmcnt(8)
	v_pk_fma_f32 v[64:65], v[64:65], s[80:81], v[156:157] op_sel_hi:[1,0,0]
	v_pk_fma_f32 v[60:61], v[60:61], s[80:81], v[156:157] op_sel_hi:[1,0,0]
	v_pk_fma_f32 v[62:63], v[62:63], s[80:81], v[156:157] op_sel_hi:[1,0,0]
	v_pk_fma_f32 v[58:59], v[58:59], s[80:81], v[156:157] op_sel_hi:[1,0,0]
	s_waitcnt lgkmcnt(6)
	v_mfma_f32_32x32x16_bf16 v[34:49], v[70:73], v[98:101], v[34:49]
	v_mfma_f32_32x32x16_bf16 v[50:65], v[66:69], v[98:101], v[50:65]
	s_waitcnt lgkmcnt(5)
	v_mfma_f32_32x32x16_bf16 v[34:49], v[74:77], v[102:105], v[34:49]
	s_waitcnt lgkmcnt(4)
	v_mfma_f32_32x32x16_bf16 v[50:65], v[78:81], v[102:105], v[50:65]
	s_waitcnt lgkmcnt(3)
	v_mfma_f32_32x32x16_bf16 v[34:49], v[82:85], v[106:109], v[34:49]
	s_waitcnt lgkmcnt(2)
	v_mfma_f32_32x32x16_bf16 v[50:65], v[86:89], v[106:109], v[50:65]
	s_waitcnt lgkmcnt(1)
	v_mfma_f32_32x32x16_bf16 v[34:49], v[90:93], v[110:113], v[34:49]
	s_waitcnt lgkmcnt(0)
	v_mfma_f32_32x32x16_bf16 v[50:65], v[94:97], v[110:113], v[50:65]
	v_cmp_lt_i32_e32 vcc, 0, v158
	s_mov_b32 s2, 0xefa18f08
	s_nop 6
	v_cndmask_b32_e32 v72, v210, v35, vcc
	v_cmp_lt_i32_e64 s[98:99], -1, v158
	v_cmp_lt_i32_e64 s[100:101], 32, v158
	v_cmp_lt_i32_e32 vcc, 31, v158
	v_cndmask_b32_e64 v76, v210, v34, s[98:99]
	v_cndmask_b32_e64 v66, v210, v51, s[100:101]
	v_cndmask_b32_e32 v68, v210, v50, vcc
	v_cmp_lt_i32_e64 s[98:99], 2, v158
	v_cmp_lt_i32_e64 s[100:101], 1, v158
	v_cmp_lt_i32_e32 vcc, 34, v158
	v_cndmask_b32_e64 v71, v210, v37, s[98:99]
	v_cndmask_b32_e64 v75, v210, v36, s[100:101]
	v_cndmask_b32_e32 v53, v210, v53, vcc
	v_cmp_lt_i32_e64 s[98:99], 33, v158
	v_cmp_lt_i32_e64 s[100:101], 4, v158
	v_cmp_lt_i32_e32 vcc, 3, v158
	v_cndmask_b32_e64 v67, v210, v52, s[98:99]
	v_cndmask_b32_e64 v70, v210, v39, s[100:101]
	v_cndmask_b32_e32 v74, v210, v38, vcc
	v_cmp_lt_i32_e64 s[98:99], 36, v158
	v_cmp_lt_i32_e64 s[100:101], 35, v158
	v_cmp_lt_i32_e32 vcc, 6, v158
	v_cndmask_b32_e64 v51, v210, v55, s[98:99]
	v_cndmask_b32_e64 v54, v210, v54, s[100:101]
	v_cndmask_b32_e32 v69, v210, v41, vcc
	v_cmp_lt_i32_e64 s[98:99], 5, v158
	v_cmp_lt_i32_e64 s[100:101], 38, v158
	v_cmp_lt_i32_e32 vcc, 37, v158
	v_cndmask_b32_e64 v73, v210, v40, s[98:99]
	v_cndmask_b32_e64 v50, v210, v57, s[100:101]
	v_cndmask_b32_e32 v52, v210, v56, vcc
	v_cmp_lt_i32_e64 s[98:99], 16, v158
	v_cmp_lt_i32_e64 s[100:101], 15, v158
	v_cmp_lt_i32_e32 vcc, 48, v158
	v_cndmask_b32_e64 v55, v210, v43, s[98:99]
	v_cndmask_b32_e64 v57, v210, v42, s[100:101]
	v_cndmask_b32_e32 v38, v210, v59, vcc
	v_cmp_lt_i32_e64 s[98:99], 47, v158
	v_cmp_lt_i32_e64 s[100:101], 18, v158
	v_cmp_lt_i32_e32 vcc, 17, v158
	v_cndmask_b32_e64 v41, v210, v58, s[98:99]
	v_cndmask_b32_e64 v45, v210, v45, s[100:101]
	v_cndmask_b32_e32 v56, v210, v44, vcc
	v_cmp_lt_i32_e64 s[98:99], 50, v158
	v_cmp_lt_i32_e64 s[100:101], 49, v158
	v_cmp_lt_i32_e32 vcc, 20, v158
	v_cndmask_b32_e64 v36, v210, v61, s[98:99]
	v_cndmask_b32_e64 v40, v210, v60, s[100:101]
	v_cndmask_b32_e32 v43, v210, v47, vcc
	v_cmp_lt_i32_e64 s[98:99], 19, v158
	v_cmp_lt_i32_e64 s[100:101], 52, v158
	v_cmp_lt_i32_e32 vcc, 51, v158
	v_cndmask_b32_e64 v46, v210, v46, s[98:99]
	v_cndmask_b32_e64 v35, v210, v63, s[100:101]
	v_cndmask_b32_e32 v39, v210, v62, vcc
	v_cmp_lt_i32_e32 vcc, 22, v158
	s_nop 1
	v_cndmask_b32_e32 v42, v210, v49, vcc
	v_cmp_lt_i32_e32 vcc, 21, v158
	v_and_b32_e32 v49, 64, v209
	v_add_u32_e32 v49, 64, v49
	v_cndmask_b32_e32 v44, v210, v48, vcc
	v_cmp_lt_i32_e32 vcc, 54, v158
	v_max_f32_e32 v48, v42, v42
	s_nop 0
	v_cndmask_b32_e32 v34, v210, v65, vcc
	v_max_f32_e32 v47, v34, v34
	v_min_f32_e32 v47, v48, v47
	v_max3_f32 v48, v47, v76, v68
	v_max3_f32 v47, v47, v72, v66
	v_cmp_lt_i32_e32 vcc, 53, v158
	v_max3_f32 v48, v48, v75, v67
	v_max3_f32 v47, v47, v71, v53
	v_max3_f32 v48, v48, v74, v54
	v_max3_f32 v47, v47, v70, v51
	s_nop 0
	v_cndmask_b32_e32 v37, v210, v64, vcc
	v_max3_f32 v48, v48, v73, v52
	v_max3_f32 v47, v47, v69, v50
	v_max3_f32 v48, v48, v57, v41
	v_max3_f32 v47, v47, v55, v38
	v_max3_f32 v48, v48, v56, v40
	v_max3_f32 v47, v47, v45, v36
	v_max3_f32 v48, v48, v46, v39
	v_max3_f32 v47, v47, v43, v35
	v_max3_f32 v48, v48, v44, v37
	v_max3_f32 v47, v47, v42, v34
	v_max_f32_e32 v47, v47, v47
	v_max_f32_e32 v48, v48, v48
	v_max_f32_e32 v47, v48, v47
	v_mov_b32_e32 v48, v47
	s_nop 1
	v_permlane32_swap_b32_e32 v48, v47
	s_waitcnt lgkmcnt(0)
	v_max_f32_e32 v47, v47, v48
	v_cmp_lt_f32_e64 s[26:27], s2, v47
	s_mov_b32 s2, 0x41000000
	v_cmp_lt_f32_e32 vcc, s2, v47
	s_mov_b32 s2, 0xc1000000
	v_cmp_gt_f32_e64 s[2:3], s2, v47
	s_and_b64 s[2:3], s[2:3], s[26:27]
	s_andn2_b64 s[2:3], s[2:3], s[22:23]
	s_or_b64 s[2:3], s[2:3], vcc
	s_and_b64 vcc, exec, s[2:3]
	s_cbranch_vccnz .LBB0_515

; template <int MODE>
; DI void bias_init(f32x16& s0, f32x16& s1, const TP& tp, float fbm, int hi) {
; #pragma unroll
;     for (int r = 0; r < 16; ++r) {
;         const int kvc = 16 * (r >> 3) + (r & 7);
;         if (MODE == 0) { s0[r] = __builtin_fmaf(-L2E, tp.cs[kvc + 8 * hi], fbm); s1[r] = __builtin_fmaf(-L2E, tp.cs[kvc + 32 + 8 * hi], fbm); }
;         else { s0[r] = __builtin_fmaf(tp.sl, (float)kvc, fbm); s1[r] = __builtin_fmaf(tp.sl, (float)(kvc + 32), fbm); }
;     }
; }
; DI float max3_asm(float a, float b, float c) { float r; asm("v_max3_f32 %0, %1, %2, %3" : "=v"(r) : "v"(a), "v"(b), "v"(c)); return r; }
; template <bool MASK>
; DI float mask_rowmax(f32x16& s0, f32x16& s1, const TP& tp) {
;     if (MASK) {
; #pragma unroll
;         for (int r = 0; r < 16; ++r) {
;             const int kvc = 16 * (r >> 3) + (r & 7);
;             const bool v0 = tp.sel && (kvc <= tp.lim) && (kvc > tp.lim2), v1 = tp.sel && (kvc + 32 <= tp.lim) && (kvc + 32 > tp.lim2);
;             s0[r] = v0 ? s0[r] : -1e30f; s1[r] = v1 ? s1[r] : -1e30f;
;         }
;     }
;     const float seed = __builtin_fminf(s0[15], s1[15]);
;     float ma = seed, mb = seed;
; #pragma unroll
;     for (int r = 0; r < 16; r += 2) { ma = max3_asm(ma, s0[r], s1[r]); mb = max3_asm(mb, s0[r + 1], s1[r + 1]); }
;     const float mx = fmaxf(ma, mb);
;     return fmaxf(mx, __shfl_xor(mx, 32));
; }
; template <int MODE, bool MASK, bool WITH_O>
; DI void attn_tile_t(lptr Kt, lptr Vt, const bf16x8 (&qf)[4], f32x16& o0, f32x16& o1, RowState& rs, const TP& tp, int lane) {
;     const int hi = lane >> 5;
;     f32x16 s0, s1;
;     bias_init<MODE>(s0, s1, tp, tp.fb - rs.mref, hi);
;     qk_acc(Kt, qf, s0, s1, lane);
;     const float mx = mask_rowmax<MASK>(s0, s1, tp);
; DI void cmpwin_unit(const Params& P, lptr L, int u, int tid, int lane, int wid) {
;     ...
;         ATT_LOOP_BEGIN(NTC, false, kb_ + (size_t)(jt * 64) * 64, vb_ + (size_t)jt * 64, (const float*)nullptr)
;             const int n0 = jt * 64;
;             TP tp; tp.cs = nullptr; tp.sl = 16.f * sl; tp.fb = sl * (float)(16 * (n0 + 8 * hi) + 31 - t); tp.lim = nlim - n0 - 8 * hi; tp.lim2 = -(1 << 30); tp.sel = true;
;             if (n0 + 63 <= nfull) attn_tile_t<1, false, false>(Kt, Vt, qf, od0, od1, rs, tp, lane);
;             else attn_tile_t<1, true, false>(Kt, Vt, qf, od0, od1, rs, tp, lane);
.LBB0_526:
	v_cvt_f32_i32_e32 v2, v47
	s_and_b32 s43, s30, 1
	s_mul_i32 s2, s43, 0x2400
	s_add_i32 s52, s2, 0
	v_mul_f32_e32 v50, v150, v2
	s_cmp_gt_i32 s42, s29
	s_mov_b64 s[2:3], -1
	s_cbranch_scc1 .LBB0_535
	s_mov_b32 s2, 2.0
	v_sub_f32_e32 v2, v50, v49
	s_mov_b32 s3, 0x40400000
	v_add3_u32 v51, s52, v131, v133
	v_pk_fma_f32 v[20:21], v[80:81], s[2:3], v[2:3] op_sel_hi:[1,1,0]
	s_mov_b32 s2, 4.0
	ds_read_b128 v[52:55], v51 offset:4608
	ds_read_b128 v[56:59], v51
	ds_read_b128 v[60:63], v51 offset:32
	ds_read_b128 v[64:67], v51 offset:4640
	ds_read_b128 v[68:71], v51 offset:64
	ds_read_b128 v[88:91], v51 offset:4672
	ds_read_b128 v[92:95], v51 offset:96
	ds_read_b128 v[114:117], v51 offset:4704
	s_mov_b32 s3, 0x40a00000
	v_pk_fma_f32 v[22:23], v[80:81], s[2:3], v[2:3] op_sel_hi:[1,1,0]
	s_mov_b32 s2, 0x40c00000
	s_mov_b32 s3, 0x40e00000
	v_pk_fma_f32 v[24:25], v[80:81], s[2:3], v[2:3] op_sel_hi:[1,1,0]
	s_mov_b32 s2, 0x41800000
	s_mov_b32 s3, 0x41880000
	v_pk_fma_f32 v[26:27], v[80:81], s[2:3], v[2:3] op_sel_hi:[1,1,0]
	s_mov_b32 s2, 0x41900000
	s_mov_b32 s3, 0x41980000
	v_pk_fma_f32 v[28:29], v[80:81], s[2:3], v[2:3] op_sel_hi:[1,1,0]
	s_mov_b32 s2, 0x41a00000
	s_mov_b32 s3, 0x41a80000
	v_mov_b32_e32 v79, v78
	v_fma_f32 v18, 0, v78, v2
	v_add_f32_e32 v19, v78, v2
	v_pk_fma_f32 v[30:31], v[80:81], s[2:3], v[2:3] op_sel_hi:[1,1,0]
	v_pk_fma_f32 v[32:33], v[80:81], s[18:19], v[2:3] op_sel_hi:[1,1,0]
	v_pk_fma_f32 v[16:17], v[78:79], s[4:5], v[2:3] op_sel_hi:[1,1,0]
	v_pk_fma_f32 v[14:15], v[78:79], s[14:15], v[2:3] op_sel_hi:[1,1,0]
	v_pk_fma_f32 v[12:13], v[78:79], s[16:17], v[2:3] op_sel_hi:[1,1,0]
	v_pk_fma_f32 v[10:11], v[78:79], s[94:95], v[2:3] op_sel_hi:[1,1,0]
	v_pk_fma_f32 v[8:9], v[78:79], s[96:97], v[2:3] op_sel_hi:[1,1,0]
	v_pk_fma_f32 v[6:7], v[78:79], s[84:85], v[2:3] op_sel_hi:[1,1,0]
	v_pk_fma_f32 v[4:5], v[78:79], s[72:73], v[2:3] op_sel_hi:[1,1,0]
	v_pk_fma_f32 v[2:3], v[82:83], s[44:45], v[2:3] op_sel_hi:[1,1,0]
	s_waitcnt vmcnt(4) lgkmcnt(6)
	v_mfma_f32_32x32x16_bf16 v[18:33], v[56:59], v[98:101], v[18:33]
	v_mfma_f32_32x32x16_bf16 v[2:17], v[52:55], v[98:101], v[2:17]
	s_waitcnt vmcnt(3) lgkmcnt(5)
	v_mfma_f32_32x32x16_bf16 v[18:33], v[60:63], v[102:105], v[18:33]
	s_waitcnt lgkmcnt(4)
	v_mfma_f32_32x32x16_bf16 v[2:17], v[64:67], v[102:105], v[2:17]
	s_waitcnt vmcnt(2) lgkmcnt(3)
	v_mfma_f32_32x32x16_bf16 v[18:33], v[68:71], v[106:109], v[18:33]
	s_waitcnt lgkmcnt(2)
	v_mfma_f32_32x32x16_bf16 v[2:17], v[88:91], v[106:109], v[2:17]
	s_waitcnt vmcnt(1) lgkmcnt(1)
	v_mfma_f32_32x32x16_bf16 v[18:33], v[92:95], v[110:113], v[18:33]
	s_waitcnt lgkmcnt(0)
	v_mfma_f32_32x32x16_bf16 v[2:17], v[114:117], v[110:113], v[2:17]
	s_nop 10
	v_max_f32_e32 v51, v17, v17
	v_max_f32_e32 v52, v33, v33
	v_min_f32_e32 v51, v52, v51
	v_max3_f32 v52, v51, v18, v2
	v_max3_f32 v51, v51, v19, v3
	v_and_b32_e32 v53, 64, v209
	v_max3_f32 v52, v52, v20, v4
	v_max3_f32 v51, v51, v21, v5
	v_add_u32_e32 v53, 64, v53
	v_max3_f32 v52, v52, v22, v6
	v_max3_f32 v51, v51, v23, v7
	s_mov_b32 s2, 0xefa18f08
	v_max3_f32 v52, v52, v24, v8
	v_max3_f32 v51, v51, v25, v9
	s_mov_b64 s[26:27], -1
	v_max3_f32 v52, v52, v26, v10
	v_max3_f32 v51, v51, v27, v11
	v_max3_f32 v52, v52, v28, v12
	v_max3_f32 v51, v51, v29, v13
	v_max3_f32 v52, v52, v30, v14
	v_max3_f32 v51, v51, v31, v15
	v_max3_f32 v52, v52, v32, v16
	v_max3_f32 v51, v51, v33, v17
	v_max_f32_e32 v51, v51, v51
	v_max_f32_e32 v52, v52, v52
	v_max_f32_e32 v51, v52, v51
	v_mov_b32_e32 v52, v51
	s_nop 1
	v_permlane32_swap_b32_e32 v52, v51
	s_waitcnt lgkmcnt(0)
	v_max_f32_e32 v53, v51, v52
	v_cmp_lt_f32_e64 s[24:25], s2, v53
	s_mov_b32 s2, 0x41000000
	v_cmp_lt_f32_e32 vcc, s2, v53
	s_mov_b32 s26, 0xc1000000
	v_cmp_gt_f32_e64 s[26:27], s26, v53
	s_and_b64 s[26:27], s[26:27], s[24:25]
	s_andn2_b64 s[26:27], s[26:27], s[0:1]
	s_or_b64 s[26:27], s[26:27], vcc
	s_and_b64 vcc, exec, s[26:27]
	v_mov_b32_e32 v51, v49
	v_mov_b32_e32 v52, v46
	s_cbranch_vccnz .LBB0_540

; DI float max3_asm(float a, float b, float c) { float r; asm("v_max3_f32 %0, %1, %2, %3" : "=v"(r) : "v"(a), "v"(b), "v"(c)); return r; }
; template <bool MASK>
; DI float mask_rowmax(f32x16& s0, f32x16& s1, const TP& tp) {
;     if (MASK) {
; #pragma unroll
;         for (int r = 0; r < 16; ++r) {
;             const int kvc = 16 * (r >> 3) + (r & 7);
;             const bool v0 = tp.sel && (kvc <= tp.lim) && (kvc > tp.lim2), v1 = tp.sel && (kvc + 32 <= tp.lim) && (kvc + 32 > tp.lim2);
;             s0[r] = v0 ? s0[r] : -1e30f; s1[r] = v1 ? s1[r] : -1e30f;
;         }
;     }
;     const float seed = __builtin_fminf(s0[15], s1[15]);
;     float ma = seed, mb = seed;
; #pragma unroll
;     for (int r = 0; r < 16; r += 2) { ma = max3_asm(ma, s0[r], s1[r]); mb = max3_asm(mb, s0[r + 1], s1[r + 1]); }
;     const float mx = fmaxf(ma, mb);
;     return fmaxf(mx, __shfl_xor(mx, 32));
; }
; template <int MODE, bool MASK, bool WITH_O>
; DI void attn_tile_t(lptr Kt, lptr Vt, const bf16x8 (&qf)[4], f32x16& o0, f32x16& o1, RowState& rs, const TP& tp, int lane) {
;     const int hi = lane >> 5;
;     f32x16 s0, s1;
;     bias_init<MODE>(s0, s1, tp, tp.fb - rs.mref, hi);
;     qk_acc(Kt, qf, s0, s1, lane);
;     const float mx = mask_rowmax<MASK>(s0, s1, tp);
;     const bool was = rs.seen; rs.seen = was || (mx > -1e29f);
;     const bool trig = (mx > 8.f) || (!was && mx > -1e29f && mx < -8.f);
;     if (__builtin_expect(__any(trig), 0)) {
; DI void cmpwin_unit(const Params& P, lptr L, int u, int tid, int lane, int wid) {
;     ...
;         ATT_LOOP_BEGIN(NTC, false, kb_ + (size_t)(jt * 64) * 64, vb_ + (size_t)jt * 64, (const float*)nullptr)
;             const int n0 = jt * 64;
;             TP tp; tp.cs = nullptr; tp.sl = 16.f * sl; tp.fb = sl * (float)(16 * (n0 + 8 * hi) + 31 - t); tp.lim = nlim - n0 - 8 * hi; tp.lim2 = -(1 << 30); tp.sel = true;
;             if (n0 + 63 <= nfull) attn_tile_t<1, false, false>(Kt, Vt, qf, od0, od1, rs, tp, lane);
;             else attn_tile_t<1, true, false>(Kt, Vt, qf, od0, od1, rs, tp, lane);
.LBB0_535:
	s_and_b64 vcc, exec, s[2:3]
	s_cbranch_vccz .LBB0_531
	v_sub_f32_e32 v18, v50, v49
	v_add3_u32 v232, s52, v131, v133
	ds_read_b128 v[50:53], v232 offset:4608
	ds_read_b128 v[54:57], v232
	ds_read_b128 v[58:61], v232 offset:32
	ds_read_b128 v[62:65], v232 offset:4640
	ds_read_b128 v[66:69], v232 offset:64
	ds_read_b128 v[70:73], v232 offset:4672
	ds_read_b128 v[88:91], v232 offset:96
	ds_read_b128 v[92:95], v232 offset:4704
	s_mov_b32 s2, 2.0
	v_mov_b32_e32 v79, v78
	s_mov_b32 s3, 0x40400000
	v_pk_fma_f32 v[32:33], v[78:79], s[4:5], v[18:19] op_sel_hi:[1,1,0]
	v_pk_fma_f32 v[30:31], v[78:79], s[14:15], v[18:19] op_sel_hi:[1,1,0]
	v_pk_fma_f32 v[28:29], v[78:79], s[16:17], v[18:19] op_sel_hi:[1,1,0]
	v_pk_fma_f32 v[26:27], v[78:79], s[94:95], v[18:19] op_sel_hi:[1,1,0]
	v_pk_fma_f32 v[24:25], v[78:79], s[96:97], v[18:19] op_sel_hi:[1,1,0]
	v_pk_fma_f32 v[22:23], v[78:79], s[84:85], v[18:19] op_sel_hi:[1,1,0]
	v_pk_fma_f32 v[20:21], v[78:79], s[72:73], v[18:19] op_sel_hi:[1,1,0]
	v_pk_fma_f32 v[4:5], v[80:81], s[2:3], v[18:19] op_sel_hi:[1,1,0]
	s_mov_b32 s2, 4.0
	s_mov_b32 s3, 0x40a00000
	v_pk_fma_f32 v[6:7], v[80:81], s[2:3], v[18:19] op_sel_hi:[1,1,0]
	s_mov_b32 s2, 0x40c00000
	s_mov_b32 s3, 0x40e00000
	v_pk_fma_f32 v[8:9], v[80:81], s[2:3], v[18:19] op_sel_hi:[1,1,0]
	s_mov_b32 s2, 0x41800000
	s_mov_b32 s3, 0x41880000
	v_pk_fma_f32 v[10:11], v[80:81], s[2:3], v[18:19] op_sel_hi:[1,1,0]
	s_mov_b32 s2, 0x41900000
	s_mov_b32 s3, 0x41980000
	v_pk_fma_f32 v[12:13], v[80:81], s[2:3], v[18:19] op_sel_hi:[1,1,0]
	s_mov_b32 s2, 0x41a00000
	s_mov_b32 s3, 0x41a80000
	v_fma_f32 v2, 0, v78, v18
	v_add_f32_e32 v3, v78, v18
	v_pk_fma_f32 v[14:15], v[80:81], s[2:3], v[18:19] op_sel_hi:[1,1,0]
	v_pk_fma_f32 v[16:17], v[80:81], s[18:19], v[18:19] op_sel_hi:[1,1,0]
	v_pk_fma_f32 v[18:19], v[82:83], s[44:45], v[18:19] op_sel_hi:[1,1,0]
	s_waitcnt vmcnt(4) lgkmcnt(6)
	v_mfma_f32_32x32x16_bf16 v[2:17], v[54:57], v[98:101], v[2:17]
	v_mfma_f32_32x32x16_bf16 v[18:33], v[50:53], v[98:101], v[18:33]
	s_waitcnt vmcnt(3) lgkmcnt(5)
	v_mfma_f32_32x32x16_bf16 v[2:17], v[58:61], v[102:105], v[2:17]
	s_waitcnt lgkmcnt(4)
	v_mfma_f32_32x32x16_bf16 v[18:33], v[62:65], v[102:105], v[18:33]
	s_waitcnt vmcnt(2) lgkmcnt(3)
	v_mfma_f32_32x32x16_bf16 v[2:17], v[66:69], v[106:109], v[2:17]
	s_waitcnt lgkmcnt(2)
	v_mfma_f32_32x32x16_bf16 v[18:33], v[70:73], v[106:109], v[18:33]
	s_waitcnt vmcnt(1) lgkmcnt(1)
	v_mfma_f32_32x32x16_bf16 v[2:17], v[88:91], v[110:113], v[2:17]
	s_waitcnt lgkmcnt(0)
	v_mfma_f32_32x32x16_bf16 v[18:33], v[92:95], v[110:113], v[18:33]
	v_cmp_lt_i32_e32 vcc, 0, v48
	s_mov_b32 s2, 0xefa18f08
	s_nop 6
	v_cndmask_b32_e32 v51, v210, v3, vcc
	v_cmp_lt_i32_e64 s[98:99], -1, v48
	v_cmp_lt_i32_e64 s[100:101], 32, v48
	v_cmp_lt_i32_e32 vcc, 31, v48
	v_cndmask_b32_e64 v55, v210, v2, s[98:99]
	v_cndmask_b32_e64 v53, v210, v19, s[100:101]
	v_cndmask_b32_e32 v58, v210, v18, vcc
	v_cmp_lt_i32_e64 s[98:99], 2, v48
	v_cmp_lt_i32_e64 s[100:101], 1, v48
	v_cmp_lt_i32_e32 vcc, 34, v48
	v_cndmask_b32_e64 v50, v210, v5, s[98:99]
	v_cndmask_b32_e64 v57, v210, v4, s[100:101]
	v_cndmask_b32_e32 v21, v210, v21, vcc
	v_cmp_lt_i32_e64 s[98:99], 33, v48
	v_cmp_lt_i32_e64 s[100:101], 4, v48
	v_cmp_lt_i32_e32 vcc, 3, v48
	v_cndmask_b32_e64 v59, v210, v20, s[98:99]
	v_cndmask_b32_e64 v18, v210, v7, s[100:101]
	v_cndmask_b32_e32 v54, v210, v6, vcc
	v_cmp_lt_i32_e64 s[98:99], 36, v48
	v_cmp_lt_i32_e64 s[100:101], 35, v48
	v_cmp_lt_i32_e32 vcc, 6, v48
	v_cndmask_b32_e64 v20, v210, v23, s[98:99]
	v_cndmask_b32_e64 v56, v210, v22, s[100:101]
	v_cndmask_b32_e32 v9, v210, v9, vcc
	v_cmp_lt_i32_e64 s[98:99], 5, v48
	v_cmp_lt_i32_e64 s[100:101], 38, v48
	v_cmp_lt_i32_e32 vcc, 37, v48
	v_cndmask_b32_e64 v52, v210, v8, s[98:99]
	v_cndmask_b32_e64 v19, v210, v25, s[100:101]
	v_cndmask_b32_e32 v25, v210, v24, vcc
	v_cmp_lt_i32_e64 s[98:99], 16, v48
	v_cmp_lt_i32_e64 s[100:101], 15, v48
	v_cmp_lt_i32_e32 vcc, 48, v48
	v_cndmask_b32_e64 v6, v210, v11, s[98:99]
	v_cndmask_b32_e64 v22, v210, v10, s[100:101]
	v_cndmask_b32_e32 v8, v210, v27, vcc
	v_cmp_lt_i32_e32 vcc, 47, v48
	s_nop 1
	v_cndmask_b32_e32 v24, v210, v26, vcc
	v_cmp_lt_i32_e32 vcc, 18, v48
	v_and_b32_e32 v26, 64, v209
	v_add_u32_e32 v26, 64, v26
	v_cndmask_b32_e32 v4, v210, v13, vcc
	v_cmp_lt_i32_e64 s[98:99], 17, v48
	v_cmp_lt_i32_e64 s[100:101], 50, v48
	v_cmp_lt_i32_e32 vcc, 49, v48
	v_cndmask_b32_e64 v13, v210, v12, s[98:99]
	v_cndmask_b32_e64 v7, v210, v29, s[100:101]
	v_cndmask_b32_e32 v23, v210, v28, vcc
	v_cmp_lt_i32_e64 s[98:99], 20, v48
	v_cmp_lt_i32_e64 s[100:101], 19, v48
	v_cmp_lt_i32_e32 vcc, 52, v48
	v_cndmask_b32_e64 v3, v210, v15, s[98:99]
	v_cndmask_b32_e64 v11, v210, v14, s[100:101]
	v_cndmask_b32_e32 v5, v210, v31, vcc
	v_cmp_lt_i32_e64 s[98:99], 51, v48
	v_cmp_lt_i32_e64 s[100:101], 22, v48
	v_cmp_lt_i32_e32 vcc, 21, v48
	v_cndmask_b32_e64 v14, v210, v30, s[98:99]
	v_cndmask_b32_e64 v2, v210, v17, s[100:101]
	v_cndmask_b32_e32 v10, v210, v16, vcc
	v_cmp_lt_i32_e32 vcc, 54, v48
	v_max_f32_e32 v16, v2, v2
	s_nop 0
	v_cndmask_b32_e32 v17, v210, v33, vcc
	v_max_f32_e32 v15, v17, v17
	v_min_f32_e32 v15, v16, v15
	v_max3_f32 v16, v15, v55, v58
	v_max3_f32 v15, v15, v51, v53
	v_cmp_lt_i32_e32 vcc, 53, v48
	v_max3_f32 v16, v16, v57, v59
	v_max3_f32 v15, v15, v50, v21
	v_max3_f32 v16, v16, v54, v56
	v_max3_f32 v15, v15, v18, v20
	s_nop 0
	v_cndmask_b32_e32 v12, v210, v32, vcc
	v_max3_f32 v16, v16, v52, v25
	v_max3_f32 v15, v15, v9, v19
	v_max3_f32 v16, v16, v22, v24
	v_max3_f32 v15, v15, v6, v8
	v_max3_f32 v16, v16, v13, v23
	v_max3_f32 v15, v15, v4, v7
	v_max3_f32 v16, v16, v11, v14
	v_max3_f32 v15, v15, v3, v5
	v_max3_f32 v16, v16, v10, v12
	v_max3_f32 v15, v15, v2, v17
	v_max_f32_e32 v15, v15, v15
	v_max_f32_e32 v16, v16, v16
	v_max_f32_e32 v15, v16, v15
	v_mov_b32_e32 v16, v15
	s_nop 1
	v_permlane32_swap_b32_e32 v16, v15
	s_waitcnt lgkmcnt(0)
	v_max_f32_e32 v15, v15, v16
	v_cmp_lt_f32_e64 s[24:25], s2, v15
	s_mov_b32 s2, 0x41000000
	v_cmp_lt_f32_e32 vcc, s2, v15
	s_mov_b32 s2, 0xc1000000
	v_cmp_gt_f32_e64 s[2:3], s2, v15
	s_and_b64 s[2:3], s[2:3], s[24:25]
	s_andn2_b64 s[2:3], s[2:3], s[0:1]
	s_or_b64 s[2:3], s[2:3], vcc
	s_and_b64 vcc, exec, s[2:3]
	s_cbranch_vccnz .LBB0_541

; template <int MODE>
; DI void bias_init(f32x16& s0, f32x16& s1, const TP& tp, float fbm, int hi) {
; #pragma unroll
;     for (int r = 0; r < 16; ++r) {
;         const int kvc = 16 * (r >> 3) + (r & 7);
;         if (MODE == 0) { s0[r] = __builtin_fmaf(-L2E, tp.cs[kvc + 8 * hi], fbm); s1[r] = __builtin_fmaf(-L2E, tp.cs[kvc + 32 + 8 * hi], fbm); }
;         else { s0[r] = __builtin_fmaf(tp.sl, (float)kvc, fbm); s1[r] = __builtin_fmaf(tp.sl, (float)(kvc + 32), fbm); }
;     }
; }
; DI float max3_asm(float a, float b, float c) { float r; asm("v_max3_f32 %0, %1, %2, %3" : "=v"(r) : "v"(a), "v"(b), "v"(c)); return r; }
; template <bool MASK>
; DI float mask_rowmax(f32x16& s0, f32x16& s1, const TP& tp) {
;     if (MASK) {
; #pragma unroll
;         for (int r = 0; r < 16; ++r) {
;             const int kvc = 16 * (r >> 3) + (r & 7);
;             const bool v0 = tp.sel && (kvc <= tp.lim) && (kvc > tp.lim2), v1 = tp.sel && (kvc + 32 <= tp.lim) && (kvc + 32 > tp.lim2);
;             s0[r] = v0 ? s0[r] : -1e30f; s1[r] = v1 ? s1[r] : -1e30f;
; DI void cmpwin_unit(const Params& P, lptr L, int u, int tid, int lane, int wid) {
;     ...
;         ATT_LOOP_BEGIN(NTC, false, kb_ + (size_t)(jt * 64) * 64, vb_ + (size_t)jt * 64, (const float*)nullptr)
;             const int n0 = jt * 64;
;             TP tp; tp.cs = nullptr; tp.sl = 16.f * sl; tp.fb = sl * (float)(16 * (n0 + 8 * hi) + 31 - t); tp.lim = nlim - n0 - 8 * hi; tp.lim2 = -(1 << 30); tp.sel = true;
;             f32x16 s0, s1;
;             bias_init<1>(s0, s1, tp, tp.fb - mfin, hi);
;             qk_acc(Kt, qf, s0, s1, lane);
;             if (n0 + 63 > nfull) (void)mask_rowmax<true>(s0, s1, tp);
.LBB0_548:
	s_and_b32 s25, s24, 1
	s_mul_i32 s26, s25, 0x2400
	v_add_u32_e32 v232, s26, v170
	ds_read_b128 v[90:93], v232 offset:4608
	ds_read_b128 v[94:97], v232
	ds_read_b128 v[114:117], v232 offset:32
	ds_read_b128 v[118:121], v232 offset:4640
	ds_read_b128 v[154:157], v232 offset:64
	ds_read_b128 v[158:161], v232 offset:4672
	ds_read_b128 v[162:165], v232 offset:96
	ds_read_b128 v[166:169], v232 offset:4704
	s_lshl_b32 s2, s24, 6
	v_or_b32_e32 v88, s2, v126
	v_lshlrev_b32_e32 v34, 4, v88
	v_sub_u32_e32 v34, v34, v85
	v_add_u32_e32 v34, 31, v34
	v_cvt_f32_i32_e32 v34, v34
	s_mov_b32 s22, 2.0
	v_fma_f32 v50, v150, v34, -v87
	v_mov_b32_e32 v79, v78
	s_mov_b32 s23, 0x40400000
	v_pk_fma_f32 v[64:65], v[78:79], s[4:5], v[50:51] op_sel_hi:[1,1,0]
	v_pk_fma_f32 v[62:63], v[78:79], s[14:15], v[50:51] op_sel_hi:[1,1,0]
	v_pk_fma_f32 v[60:61], v[78:79], s[16:17], v[50:51] op_sel_hi:[1,1,0]
	v_pk_fma_f32 v[58:59], v[78:79], s[94:95], v[50:51] op_sel_hi:[1,1,0]
	v_pk_fma_f32 v[56:57], v[78:79], s[96:97], v[50:51] op_sel_hi:[1,1,0]
	v_pk_fma_f32 v[54:55], v[78:79], s[84:85], v[50:51] op_sel_hi:[1,1,0]
	v_pk_fma_f32 v[52:53], v[78:79], s[72:73], v[50:51] op_sel_hi:[1,1,0]
	v_pk_fma_f32 v[36:37], v[80:81], s[22:23], v[50:51] op_sel_hi:[1,1,0]
	s_mov_b32 s22, 4.0
	s_mov_b32 s23, 0x40a00000
	v_pk_fma_f32 v[38:39], v[80:81], s[22:23], v[50:51] op_sel_hi:[1,1,0]
	s_mov_b32 s22, 0x40c00000
	s_mov_b32 s23, 0x40e00000
	v_pk_fma_f32 v[40:41], v[80:81], s[22:23], v[50:51] op_sel_hi:[1,1,0]
	s_mov_b32 s22, 0x41800000
	s_mov_b32 s23, 0x41880000
	v_pk_fma_f32 v[42:43], v[80:81], s[22:23], v[50:51] op_sel_hi:[1,1,0]
	s_mov_b32 s22, 0x41900000
	s_mov_b32 s23, 0x41980000
	v_pk_fma_f32 v[44:45], v[80:81], s[22:23], v[50:51] op_sel_hi:[1,1,0]
	s_mov_b32 s22, 0x41a00000
	s_mov_b32 s23, 0x41a80000
	v_fma_f32 v34, 0, v78, v50
	v_add_f32_e32 v35, v78, v50
	v_pk_fma_f32 v[46:47], v[80:81], s[22:23], v[50:51] op_sel_hi:[1,1,0]
	v_pk_fma_f32 v[48:49], v[80:81], s[18:19], v[50:51] op_sel_hi:[1,1,0]
	v_pk_fma_f32 v[50:51], v[82:83], s[44:45], v[50:51] op_sel_hi:[1,1,0]
	s_waitcnt lgkmcnt(6)
	v_mfma_f32_32x32x16_bf16 v[34:49], v[94:97], v[98:101], v[34:49]
	v_mfma_f32_32x32x16_bf16 v[50:65], v[90:93], v[98:101], v[50:65]
	s_waitcnt lgkmcnt(5)
	v_mfma_f32_32x32x16_bf16 v[34:49], v[114:117], v[102:105], v[34:49]
	s_waitcnt lgkmcnt(4)
	v_mfma_f32_32x32x16_bf16 v[50:65], v[118:121], v[102:105], v[50:65]
	s_waitcnt lgkmcnt(3)
	v_mfma_f32_32x32x16_bf16 v[34:49], v[154:157], v[106:109], v[34:49]
	s_waitcnt lgkmcnt(2)
	v_mfma_f32_32x32x16_bf16 v[50:65], v[158:161], v[106:109], v[50:65]
	s_waitcnt lgkmcnt(1)
	v_mfma_f32_32x32x16_bf16 v[34:49], v[162:165], v[110:113], v[34:49]
	s_waitcnt lgkmcnt(0)
	v_mfma_f32_32x32x16_bf16 v[50:65], v[166:169], v[110:113], v[50:65]
	s_or_b32 s3, s2, 63
	s_cmp_le_i32 s3, s29
	s_cbranch_scc1 .LBB0_550
	v_sub_u32_e32 v79, v86, v88
	v_cmp_lt_i32_e32 vcc, -1, v79
	s_nop 3
	v_cndmask_b32_e32 v34, v210, v34, vcc
	v_cmp_lt_i32_e64 s[98:99], 31, v79
	v_cmp_lt_i32_e64 s[100:101], 0, v79
	v_cmp_lt_i32_e32 vcc, 32, v79
	v_cndmask_b32_e64 v50, v210, v50, s[98:99]
	v_cndmask_b32_e64 v35, v210, v35, s[100:101]
	v_cndmask_b32_e32 v51, v210, v51, vcc
	v_cmp_lt_i32_e64 s[98:99], 1, v79
	v_cmp_lt_i32_e64 s[100:101], 33, v79
	v_cmp_lt_i32_e32 vcc, 2, v79
	v_cndmask_b32_e64 v36, v210, v36, s[98:99]
	v_cndmask_b32_e64 v52, v210, v52, s[100:101]
	v_cndmask_b32_e32 v37, v210, v37, vcc
	v_cmp_lt_i32_e64 s[98:99], 34, v79
	v_cmp_lt_i32_e64 s[100:101], 3, v79
	v_cmp_lt_i32_e32 vcc, 35, v79
	v_cndmask_b32_e64 v53, v210, v53, s[98:99]
	v_cndmask_b32_e64 v38, v210, v38, s[100:101]
	v_cndmask_b32_e32 v54, v210, v54, vcc
	v_cmp_lt_i32_e64 s[98:99], 4, v79
	v_cmp_lt_i32_e64 s[100:101], 36, v79
	v_cmp_lt_i32_e32 vcc, 5, v79
	v_cndmask_b32_e64 v39, v210, v39, s[98:99]
	v_cndmask_b32_e64 v55, v210, v55, s[100:101]
	v_cndmask_b32_e32 v40, v210, v40, vcc
	v_cmp_lt_i32_e64 s[98:99], 37, v79
	v_cmp_lt_i32_e64 s[100:101], 6, v79
	v_cmp_lt_i32_e32 vcc, 38, v79
	v_cndmask_b32_e64 v56, v210, v56, s[98:99]
	v_cndmask_b32_e64 v41, v210, v41, s[100:101]
	v_cndmask_b32_e32 v57, v210, v57, vcc
	v_cmp_lt_i32_e64 s[98:99], 15, v79
	v_cmp_lt_i32_e64 s[100:101], 47, v79
	v_cmp_lt_i32_e32 vcc, 16, v79
	v_cndmask_b32_e64 v42, v210, v42, s[98:99]
	v_cndmask_b32_e64 v58, v210, v58, s[100:101]
	v_cndmask_b32_e32 v43, v210, v43, vcc
	v_cmp_lt_i32_e64 s[98:99], 48, v79
	v_cmp_lt_i32_e64 s[100:101], 17, v79
	v_cmp_lt_i32_e32 vcc, 49, v79
	v_cndmask_b32_e64 v59, v210, v59, s[98:99]
	v_cndmask_b32_e64 v44, v210, v44, s[100:101]
	v_cndmask_b32_e32 v60, v210, v60, vcc
	v_cmp_lt_i32_e64 s[98:99], 18, v79
	v_cmp_lt_i32_e64 s[100:101], 50, v79
	v_cmp_lt_i32_e32 vcc, 19, v79
	v_cndmask_b32_e64 v45, v210, v45, s[98:99]
	v_cndmask_b32_e64 v61, v210, v61, s[100:101]
	v_cndmask_b32_e32 v46, v210, v46, vcc
	v_cmp_lt_i32_e64 s[98:99], 51, v79
	v_cmp_lt_i32_e64 s[100:101], 20, v79
	v_cmp_lt_i32_e32 vcc, 52, v79
	v_cndmask_b32_e64 v62, v210, v62, s[98:99]
	v_cndmask_b32_e64 v47, v210, v47, s[100:101]
	v_cndmask_b32_e32 v63, v210, v63, vcc
	v_cmp_lt_i32_e64 s[98:99], 21, v79
	v_cmp_lt_i32_e64 s[100:101], 53, v79
	v_cmp_lt_i32_e32 vcc, 22, v79
	v_cndmask_b32_e64 v48, v210, v48, s[98:99]
	v_cndmask_b32_e64 v64, v210, v64, s[100:101]
	v_cndmask_b32_e32 v49, v210, v49, vcc
	v_cmp_lt_i32_e32 vcc, 54, v79
	s_nop 1
	v_cndmask_b32_e32 v65, v210, v65, vcc

; template <int MODE>
; DI void bias_init(f32x16& s0, f32x16& s1, const TP& tp, float fbm, int hi) {
; #pragma unroll
;     for (int r = 0; r < 16; ++r) {
;         const int kvc = 16 * (r >> 3) + (r & 7);
;         if (MODE == 0) { s0[r] = __builtin_fmaf(-L2E, tp.cs[kvc + 8 * hi], fbm); s1[r] = __builtin_fmaf(-L2E, tp.cs[kvc + 32 + 8 * hi], fbm); }
;         else { s0[r] = __builtin_fmaf(tp.sl, (float)kvc, fbm); s1[r] = __builtin_fmaf(tp.sl, (float)(kvc + 32), fbm); }
;     }
; }
; DI float max3_asm(float a, float b, float c) { float r; asm("v_max3_f32 %0, %1, %2, %3" : "=v"(r) : "v"(a), "v"(b), "v"(c)); return r; }
; template <bool MASK>
; DI float mask_rowmax(f32x16& s0, f32x16& s1, const TP& tp) {
;     if (MASK) {
; #pragma unroll
;         for (int r = 0; r < 16; ++r) {
;             const int kvc = 16 * (r >> 3) + (r & 7);
;             const bool v0 = tp.sel && (kvc <= tp.lim) && (kvc > tp.lim2), v1 = tp.sel && (kvc + 32 <= tp.lim) && (kvc + 32 > tp.lim2);
;             s0[r] = v0 ? s0[r] : -1e30f; s1[r] = v1 ? s1[r] : -1e30f;
;         }
;     }
;     const float seed = __builtin_fminf(s0[15], s1[15]);
;     float ma = seed, mb = seed;
; #pragma unroll
;     for (int r = 0; r < 16; r += 2) { ma = max3_asm(ma, s0[r], s1[r]); mb = max3_asm(mb, s0[r + 1], s1[r + 1]); }
;     const float mx = fmaxf(ma, mb);
;     return fmaxf(mx, __shfl_xor(mx, 32));
; }
; template <int MODE, bool MASK, bool WITH_O>
; DI void attn_tile_t(lptr Kt, lptr Vt, const bf16x8 (&qf)[4], f32x16& o0, f32x16& o1, RowState& rs, const TP& tp, int lane) {
;     const int hi = lane >> 5;
;     f32x16 s0, s1;
;     bias_init<MODE>(s0, s1, tp, tp.fb - rs.mref, hi);
;     qk_acc(Kt, qf, s0, s1, lane);
;     const float mx = mask_rowmax<MASK>(s0, s1, tp);
;     const bool was = rs.seen; rs.seen = was || (mx > -1e29f);
; DI void cmpwin_unit(const Params& P, lptr L, int u, int tid, int lane, int wid) {
;     ...
;         ATT_LOOP_BEGIN(NTW, false, kb_ + (size_t)((jw0 + jt) * 64) * PROJ_LD, vb_ + (size_t)(jw0 + jt) * 64, (const float*)nullptr)
;             const int kv0 = (jw0 + jt) * 64;
;             TP tp; tp.cs = nullptr; tp.sl = sl; tp.fb = sl * (float)(kv0 + 8 * hi - t); tp.lim = t - kv0 - 8 * hi; tp.lim2 = tp.lim - 512; tp.sel = true;
;             const bool full = (kv0 + 63 <= tq0) && (tq0 + 31 - kv0 < 512);
;             attn_tile<1>(Kt, Vt, qf, o0, o1, rs, tp, !full, lane);
.LBB0_581:
	s_and_b32 s54, s53, 1
	s_mul_i32 s2, s54, 0x2400
	v_add_u32_e32 v34, s43, v161
	s_add_i32 s55, s2, 0
	s_add_i32 s2, s43, 63
	v_cvt_f32_i32_e32 v34, v34
	s_cmp_gt_u32 s2, s81
	s_cselect_b64 s[2:3], -1, 0
	s_cmp_lt_i32 s43, s23
	s_cselect_b64 s[28:29], -1, 0
	s_or_b64 s[2:3], s[2:3], s[28:29]
	v_mul_f32_e32 v216, v150, v34
	s_andn2_b64 vcc, exec, s[2:3]
	s_mov_b64 s[2:3], -1
	s_cbranch_vccz .LBB0_590
	v_add3_u32 v234, s55, v131, v133
	ds_read_b128 v[34:37], v234 offset:4608
	ds_read_b128 v[38:41], v234
	ds_read_b128 v[42:45], v234 offset:32
	ds_read_b128 v[46:49], v234 offset:4640
	ds_read_b128 v[50:53], v234 offset:64
	ds_read_b128 v[54:57], v234 offset:4672
	ds_read_b128 v[58:61], v234 offset:96
	ds_read_b128 v[62:65], v234 offset:4704
	s_mov_b32 s2, 2.0
	v_sub_f32_e32 v232, v216, v215
	s_mov_b32 s3, 0x40400000
	v_pk_fma_f32 v[84:85], v[166:167], s[2:3], v[232:233] op_sel_hi:[1,1,0]
	s_mov_b32 s2, 4.0
	s_mov_b32 s3, 0x40a00000
	v_pk_fma_f32 v[86:87], v[166:167], s[2:3], v[232:233] op_sel_hi:[1,1,0]
	s_mov_b32 s2, 0x40c00000
	s_mov_b32 s3, 0x40e00000
	v_pk_fma_f32 v[88:89], v[166:167], s[2:3], v[232:233] op_sel_hi:[1,1,0]
	s_mov_b32 s2, 0x41800000
	s_mov_b32 s3, 0x41880000
	v_pk_fma_f32 v[90:91], v[166:167], s[2:3], v[232:233] op_sel_hi:[1,1,0]
	s_mov_b32 s2, 0x41900000
	s_mov_b32 s3, 0x41980000
	v_pk_fma_f32 v[92:93], v[166:167], s[2:3], v[232:233] op_sel_hi:[1,1,0]
	s_mov_b32 s2, 0x41a00000
	s_mov_b32 s3, 0x41a80000
	v_mov_b32_e32 v151, v150
	v_fma_f32 v82, 0, v150, v232
	v_add_f32_e32 v83, v150, v232
	v_pk_fma_f32 v[94:95], v[166:167], s[2:3], v[232:233] op_sel_hi:[1,1,0]
	v_pk_fma_f32 v[96:97], v[166:167], s[18:19], v[232:233] op_sel_hi:[1,1,0]
	v_pk_fma_f32 v[80:81], v[150:151], s[4:5], v[232:233] op_sel_hi:[1,1,0]
	v_pk_fma_f32 v[78:79], v[150:151], s[14:15], v[232:233] op_sel_hi:[1,1,0]
	v_pk_fma_f32 v[76:77], v[150:151], s[16:17], v[232:233] op_sel_hi:[1,1,0]
	v_pk_fma_f32 v[74:75], v[150:151], s[94:95], v[232:233] op_sel_hi:[1,1,0]
	v_pk_fma_f32 v[72:73], v[150:151], s[96:97], v[232:233] op_sel_hi:[1,1,0]
	v_pk_fma_f32 v[70:71], v[150:151], s[84:85], v[232:233] op_sel_hi:[1,1,0]
	v_pk_fma_f32 v[68:69], v[150:151], s[72:73], v[232:233] op_sel_hi:[1,1,0]
	v_pk_fma_f32 v[66:67], v[168:169], s[44:45], v[232:233] op_sel_hi:[1,1,0]
	s_waitcnt lgkmcnt(6)
	v_mfma_f32_32x32x16_bf16 v[82:97], v[38:41], v[98:101], v[82:97]
	v_mfma_f32_32x32x16_bf16 v[66:81], v[34:37], v[98:101], v[66:81]
	s_waitcnt lgkmcnt(5)
	v_mfma_f32_32x32x16_bf16 v[82:97], v[42:45], v[102:105], v[82:97]
	s_waitcnt lgkmcnt(4)
	v_mfma_f32_32x32x16_bf16 v[66:81], v[46:49], v[102:105], v[66:81]
	s_waitcnt lgkmcnt(3)
	v_mfma_f32_32x32x16_bf16 v[82:97], v[50:53], v[106:109], v[82:97]
	s_waitcnt lgkmcnt(2)
	v_mfma_f32_32x32x16_bf16 v[66:81], v[54:57], v[106:109], v[66:81]
	s_waitcnt lgkmcnt(1)
	v_mfma_f32_32x32x16_bf16 v[82:97], v[58:61], v[110:113], v[82:97]
	s_waitcnt lgkmcnt(0)
	v_mfma_f32_32x32x16_bf16 v[66:81], v[62:65], v[110:113], v[66:81]
	s_nop 10
	v_max_f32_e32 v34, v81, v81
	v_max_f32_e32 v35, v97, v97
	v_min_f32_e32 v34, v35, v34
	v_max3_f32 v35, v34, v82, v66
	v_max3_f32 v34, v34, v83, v67
	s_mov_b32 s2, 0xefa18f08
	v_max3_f32 v35, v35, v84, v68
	v_max3_f32 v34, v34, v85, v69
	s_mov_b64 s[30:31], -1
	v_max3_f32 v35, v35, v86, v70
	v_max3_f32 v34, v34, v87, v71
	v_max3_f32 v35, v35, v88, v72
	v_max3_f32 v34, v34, v89, v73
	v_max3_f32 v35, v35, v90, v74
	v_max3_f32 v34, v34, v91, v75
	v_max3_f32 v35, v35, v92, v76
	v_max3_f32 v34, v34, v93, v77
	v_max3_f32 v35, v35, v94, v78
	v_max3_f32 v34, v34, v95, v79
	v_max3_f32 v35, v35, v96, v80
	v_max3_f32 v34, v34, v97, v81
	v_max_f32_e32 v34, v34, v34
	v_max_f32_e32 v35, v35, v35
	v_max_f32_e32 v34, v35, v34
	v_mov_b32_e32 v35, v34
	s_nop 1
	v_permlane32_swap_b32_e32 v35, v34
	s_waitcnt lgkmcnt(0)
	v_max_f32_e32 v218, v34, v35
	v_cmp_lt_f32_e64 s[28:29], s2, v218
	s_mov_b32 s2, 0x41000000
	v_cmp_lt_f32_e32 vcc, s2, v218
	s_mov_b32 s30, 0xc1000000
	v_cmp_gt_f32_e64 s[30:31], s30, v218
	s_and_b64 s[30:31], s[30:31], s[28:29]
	s_andn2_b64 s[30:31], s[30:31], s[24:25]
	s_or_b64 s[30:31], s[30:31], vcc
	s_and_b64 vcc, exec, s[30:31]
	v_mov_b32_e32 v217, v163
	v_mov_b32_e32 v151, v215
	s_cbranch_vccnz .LBB0_595

; #define LAS __attribute__((address_space(3)))
; #define MFMA32(a, b, c) __builtin_amdgcn_mfma_f32_32x32x16_bf16((a), (b), (c), 0, 0, 0)
; DI void qk_acc(lptr Kt, const bf16x8 (&qf)[4], f32x16& s0, f32x16& s1, int lane) {
;     const int i = lane & 31, hi = lane >> 5;
;     const int krow = (i & 19) | ((i & 4) << 1) | ((i & 8) >> 1);
;     lptr kp = Kt + krow * KPB + hi * 16;
;     bf16x8 a0[4], a1[4];
; #pragma unroll
;     for (int d0 = 0; d0 < 4; ++d0) { a0[d0] = *(LAS bf16x8*)(kp + d0 * 32); a1[d0] = *(LAS bf16x8*)(kp + 32 * KPB + d0 * 32); }
;     __builtin_amdgcn_s_setprio(1);
; #pragma unroll
;     for (int d0 = 0; d0 < 4; ++d0) { s0 = MFMA32(a0[d0], qf[d0], s0); s1 = MFMA32(a1[d0], qf[d0], s1); }
;     __builtin_amdgcn_s_setprio(0);
; DI void cmpwin_unit(const Params& P, lptr L, int u, int tid, int lane, int wid) {
;     ...
;         ATT_LOOP_BEGIN(NTW, false, kb_ + (size_t)((jw0 + jt) * 64) * PROJ_LD, vb_ + (size_t)(jw0 + jt) * 64, (const float*)nullptr)
;             const int kv0 = (jw0 + jt) * 64;
;             TP tp; tp.cs = nullptr; tp.sl = sl; tp.fb = sl * (float)(kv0 + 8 * hi - t); tp.lim = t - kv0 - 8 * hi; tp.lim2 = tp.lim - 512; tp.sel = true;
;             const bool full = (kv0 + 63 <= tq0) && (tq0 + 31 - kv0 < 512);
;             attn_tile<1>(Kt, Vt, qf, o0, o1, rs, tp, !full, lane);
.LBB0_590:
	s_and_b64 vcc, exec, s[2:3]
	s_cbranch_vccz .LBB0_586
	s_mov_b32 s2, 2.0
	v_sub_f32_e32 v50, v216, v215
	s_mov_b32 s3, 0x40400000
	v_add3_u32 v94, s55, v131, v133
	v_pk_fma_f32 v[36:37], v[166:167], s[2:3], v[50:51] op_sel_hi:[1,1,0]
	s_mov_b32 s2, 4.0
	ds_read_b128 v[66:69], v94 offset:4608
	ds_read_b128 v[70:73], v94
	ds_read_b128 v[74:77], v94 offset:32
	ds_read_b128 v[78:81], v94 offset:4640
	ds_read_b128 v[82:85], v94 offset:64
	ds_read_b128 v[86:89], v94 offset:4672
	ds_read_b128 v[90:93], v94 offset:96
	ds_read_b128 v[94:97], v94 offset:4704
	s_mov_b32 s3, 0x40a00000
	v_pk_fma_f32 v[38:39], v[166:167], s[2:3], v[50:51] op_sel_hi:[1,1,0]
	s_mov_b32 s2, 0x40c00000
	s_mov_b32 s3, 0x40e00000
	v_pk_fma_f32 v[40:41], v[166:167], s[2:3], v[50:51] op_sel_hi:[1,1,0]
	s_mov_b32 s2, 0x41800000
	s_mov_b32 s3, 0x41880000
	v_pk_fma_f32 v[42:43], v[166:167], s[2:3], v[50:51] op_sel_hi:[1,1,0]
	s_mov_b32 s2, 0x41900000
	s_mov_b32 s3, 0x41980000
	v_pk_fma_f32 v[44:45], v[166:167], s[2:3], v[50:51] op_sel_hi:[1,1,0]
	s_mov_b32 s2, 0x41a00000
	s_mov_b32 s3, 0x41a80000
	v_mov_b32_e32 v151, v150
	v_fma_f32 v34, 0, v150, v50
	v_add_f32_e32 v35, v150, v50
	v_pk_fma_f32 v[46:47], v[166:167], s[2:3], v[50:51] op_sel_hi:[1,1,0]
	v_pk_fma_f32 v[48:49], v[166:167], s[18:19], v[50:51] op_sel_hi:[1,1,0]
	v_pk_fma_f32 v[64:65], v[150:151], s[4:5], v[50:51] op_sel_hi:[1,1,0]
	v_pk_fma_f32 v[62:63], v[150:151], s[14:15], v[50:51] op_sel_hi:[1,1,0]
	v_pk_fma_f32 v[60:61], v[150:151], s[16:17], v[50:51] op_sel_hi:[1,1,0]
	v_pk_fma_f32 v[58:59], v[150:151], s[94:95], v[50:51] op_sel_hi:[1,1,0]
	v_pk_fma_f32 v[56:57], v[150:151], s[96:97], v[50:51] op_sel_hi:[1,1,0]
	v_pk_fma_f32 v[54:55], v[150:151], s[84:85], v[50:51] op_sel_hi:[1,1,0]
	v_pk_fma_f32 v[52:53], v[150:151], s[72:73], v[50:51] op_sel_hi:[1,1,0]
	v_pk_fma_f32 v[50:51], v[168:169], s[44:45], v[50:51] op_sel_hi:[1,1,0]
	s_waitcnt lgkmcnt(6)
	v_mfma_f32_32x32x16_bf16 v[34:49], v[70:73], v[98:101], v[34:49]
	v_mfma_f32_32x32x16_bf16 v[50:65], v[66:69], v[98:101], v[50:65]
	s_waitcnt lgkmcnt(5)
	v_mfma_f32_32x32x16_bf16 v[34:49], v[74:77], v[102:105], v[34:49]
	s_waitcnt lgkmcnt(4)
	v_mfma_f32_32x32x16_bf16 v[50:65], v[78:81], v[102:105], v[50:65]
	s_waitcnt lgkmcnt(3)
	v_mfma_f32_32x32x16_bf16 v[34:49], v[82:85], v[106:109], v[34:49]
	s_waitcnt lgkmcnt(2)
	v_mfma_f32_32x32x16_bf16 v[50:65], v[86:89], v[106:109], v[50:65]
	s_waitcnt lgkmcnt(1)
	v_mfma_f32_32x32x16_bf16 v[34:49], v[90:93], v[110:113], v[34:49]
	s_waitcnt lgkmcnt(0)
; DI float max3_asm(float a, float b, float c) { float r; asm("v_max3_f32 %0, %1, %2, %3" : "=v"(r) : "v"(a), "v"(b), "v"(c)); return r; }
; template <bool MASK>
; DI float mask_rowmax(f32x16& s0, f32x16& s1, const TP& tp) {
;     if (MASK) {
; #pragma unroll
;         for (int r = 0; r < 16; ++r) {
;             const int kvc = 16 * (r >> 3) + (r & 7);
;             const bool v0 = tp.sel && (kvc <= tp.lim) && (kvc > tp.lim2), v1 = tp.sel && (kvc + 32 <= tp.lim) && (kvc + 32 > tp.lim2);
;             s0[r] = v0 ? s0[r] : -1e30f; s1[r] = v1 ? s1[r] : -1e30f;
;         }
;     }
;     const float seed = __builtin_fminf(s0[15], s1[15]);
;     float ma = seed, mb = seed;
; #pragma unroll
;     for (int r = 0; r < 16; r += 2) { ma = max3_asm(ma, s0[r], s1[r]); mb = max3_asm(mb, s0[r + 1], s1[r + 1]); }
;     const float mx = fmaxf(ma, mb);
;     return fmaxf(mx, __shfl_xor(mx, 32));
; }
; template <int MODE, bool MASK, bool WITH_O>
; DI void attn_tile_t(lptr Kt, lptr Vt, const bf16x8 (&qf)[4], f32x16& o0, f32x16& o1, RowState& rs, const TP& tp, int lane) {
;     const int hi = lane >> 5;
;     f32x16 s0, s1;
;     bias_init<MODE>(s0, s1, tp, tp.fb - rs.mref, hi);
;     qk_acc(Kt, qf, s0, s1, lane);
;     const float mx = mask_rowmax<MASK>(s0, s1, tp);
;     const bool was = rs.seen; rs.seen = was || (mx > -1e29f);
;     const bool trig = (mx > 8.f) || (!was && mx > -1e29f && mx < -8.f);
;     if (__builtin_expect(__any(trig), 0)) {
	v_mfma_f32_32x32x16_bf16 v[50:65], v[94:97], v[110:113], v[50:65]
	v_add_u32_e32 v66, -1, v155
	v_cmp_gt_u32_e32 vcc, s10, v66
	s_mov_b32 s2, 0xefa18f08
	s_nop 5
	v_cndmask_b32_e32 v68, v210, v35, vcc
	v_cmp_gt_u32_e32 vcc, s10, v155
	v_subrev_u32_e32 v35, 32, v155
	s_nop 0
	v_cndmask_b32_e32 v75, v210, v34, vcc
	v_subrev_u32_e32 v34, 33, v155
	v_cmp_gt_u32_e32 vcc, s10, v34
	v_add_u32_e32 v34, -3, v155
	s_nop 0
	v_cndmask_b32_e32 v51, v210, v51, vcc
	v_cmp_gt_u32_e32 vcc, s10, v35
	v_add_u32_e32 v35, -2, v155
	s_nop 0
	v_cndmask_b32_e32 v67, v210, v50, vcc
	v_cmp_gt_u32_e32 vcc, s10, v34
	v_subrev_u32_e32 v34, 35, v155
	s_nop 0
	v_cndmask_b32_e32 v69, v210, v37, vcc
	v_cmp_gt_u32_e32 vcc, s10, v35
	v_subrev_u32_e32 v35, 34, v155
	v_subrev_u32_e32 v37, 20, v155
	v_cndmask_b32_e32 v72, v210, v36, vcc
	v_cmp_gt_u32_e32 vcc, s10, v34
	v_add_u32_e32 v34, -5, v155
	v_subrev_u32_e32 v36, 48, v155
	v_cndmask_b32_e32 v50, v210, v53, vcc
	v_cmp_gt_u32_e32 vcc, s10, v35
	v_add_u32_e32 v35, -4, v155
	s_nop 0
	v_cndmask_b32_e32 v66, v210, v52, vcc
	v_cmp_gt_u32_e32 vcc, s10, v34
	v_subrev_u32_e32 v34, 37, v155
	s_nop 0
	v_cndmask_b32_e32 v70, v210, v39, vcc
	v_cmp_gt_u32_e32 vcc, s10, v35
	v_subrev_u32_e32 v35, 36, v155
	s_nop 0
	v_cndmask_b32_e32 v73, v210, v38, vcc
	v_cmp_gt_u32_e32 vcc, s10, v34
	v_add_u32_e32 v34, -7, v155
	s_nop 0
	v_cndmask_b32_e32 v52, v210, v55, vcc
	v_cmp_gt_u32_e32 vcc, s10, v35
	v_add_u32_e32 v35, -6, v155
	s_nop 0
	v_cndmask_b32_e32 v54, v210, v54, vcc
	v_cmp_gt_u32_e32 vcc, s10, v34
	v_subrev_u32_e32 v34, 39, v155
	s_nop 0
	v_cndmask_b32_e32 v71, v210, v41, vcc
	v_cmp_gt_u32_e32 vcc, s10, v35
	v_subrev_u32_e32 v35, 38, v155
	s_nop 0
	v_cndmask_b32_e32 v74, v210, v40, vcc
	v_cmp_gt_u32_e32 vcc, s10, v34
	v_add_u32_e32 v34, -16, v155
	v_subrev_u32_e32 v40, 22, v155
	v_cndmask_b32_e32 v53, v210, v57, vcc
	v_cmp_gt_u32_e32 vcc, s10, v35
	v_subrev_u32_e32 v35, 17, v155
	s_nop 0
	v_cndmask_b32_e32 v55, v210, v56, vcc
	v_cmp_gt_u32_e32 vcc, s10, v35
	s_nop 1
	v_cndmask_b32_e32 v43, v210, v43, vcc
	v_cmp_gt_u32_e32 vcc, s10, v34
	v_subrev_u32_e32 v34, 49, v155
	s_nop 0
	v_cndmask_b32_e32 v57, v210, v42, vcc
	v_cmp_gt_u32_e32 vcc, s10, v34
	v_subrev_u32_e32 v34, 19, v155
	s_nop 0
	v_cndmask_b32_e32 v35, v210, v59, vcc
	v_cmp_gt_u32_e32 vcc, s10, v36
	v_subrev_u32_e32 v36, 18, v155
	s_nop 0
	v_cndmask_b32_e32 v41, v210, v58, vcc
	v_cmp_gt_u32_e32 vcc, s10, v34
	v_subrev_u32_e32 v34, 51, v155
	s_nop 0
	v_cndmask_b32_e32 v42, v210, v45, vcc
	v_cmp_gt_u32_e32 vcc, s10, v36
	v_subrev_u32_e32 v36, 50, v155
	s_nop 0
	v_cndmask_b32_e32 v56, v210, v44, vcc
	v_cmp_gt_u32_e32 vcc, s10, v34
	s_nop 1
	v_cndmask_b32_e32 v34, v210, v61, vcc
	v_cmp_gt_u32_e32 vcc, s10, v36
	v_subrev_u32_e32 v36, 21, v155
	s_nop 0
	v_cndmask_b32_e32 v38, v210, v60, vcc
	v_cmp_gt_u32_e32 vcc, s10, v36
	v_subrev_u32_e32 v36, 53, v155
	s_nop 0
	v_cndmask_b32_e32 v44, v210, v47, vcc
	v_cmp_gt_u32_e32 vcc, s10, v37
	v_subrev_u32_e32 v37, 52, v155
	s_nop 0
	v_cndmask_b32_e32 v46, v210, v46, vcc
	v_cmp_gt_u32_e32 vcc, s10, v36
	s_nop 1
	v_cndmask_b32_e32 v36, v210, v63, vcc
	v_cmp_gt_u32_e32 vcc, s10, v37
	v_subrev_u32_e32 v37, 23, v155
	s_nop 0
	v_cndmask_b32_e32 v39, v210, v62, vcc
	v_cmp_gt_u32_e32 vcc, s10, v37
	v_subrev_u32_e32 v37, 55, v155
	s_nop 0
	v_cndmask_b32_e32 v45, v210, v49, vcc
	v_cmp_gt_u32_e32 vcc, s10, v40
	v_max_f32_e32 v49, v45, v45
	v_subrev_u32_e32 v40, 54, v155
	v_cndmask_b32_e32 v47, v210, v48, vcc
	v_cmp_gt_u32_e32 vcc, s10, v37
	s_nop 1
	v_cndmask_b32_e32 v37, v210, v65, vcc
	v_max_f32_e32 v48, v37, v37
	v_min_f32_e32 v48, v49, v48
	v_max3_f32 v49, v48, v75, v67
	v_max3_f32 v48, v48, v68, v51
	v_cmp_gt_u32_e32 vcc, s10, v40
	v_max3_f32 v49, v49, v72, v66
	v_max3_f32 v48, v48, v69, v50
	v_max3_f32 v49, v49, v73, v54
	v_max3_f32 v48, v48, v70, v52
	s_nop 0
	v_cndmask_b32_e32 v40, v210, v64, vcc
	v_max3_f32 v49, v49, v74, v55
	v_max3_f32 v48, v48, v71, v53
	v_max3_f32 v49, v49, v57, v41
	v_max3_f32 v48, v48, v43, v35
	v_max3_f32 v49, v49, v56, v38
	v_max3_f32 v48, v48, v42, v34
	v_max3_f32 v49, v49, v46, v39
	v_max3_f32 v48, v48, v44, v36
	v_max3_f32 v49, v49, v47, v40
	v_max3_f32 v48, v48, v45, v37
	v_max_f32_e32 v48, v48, v48
	v_max_f32_e32 v49, v49, v49
	v_max_f32_e32 v48, v49, v48
	v_mov_b32_e32 v49, v48
	s_nop 1
	v_permlane32_swap_b32_e32 v49, v48
	s_waitcnt lgkmcnt(0)
	v_max_f32_e32 v48, v48, v49
	v_cmp_lt_f32_e64 s[28:29], s2, v48
	s_mov_b32 s2, 0x41000000
	v_cmp_lt_f32_e32 vcc, s2, v48
	s_mov_b32 s2, 0xc1000000
	v_cmp_gt_f32_e64 s[2:3], s2, v48
	s_and_b64 s[2:3], s[2:3], s[28:29]
	s_andn2_b64 s[2:3], s[2:3], s[24:25]
	s_or_b64 s[2:3], s[2:3], vcc
	s_and_b64 vcc, exec, s[2:3]
	s_cbranch_vccnz .LBB0_596

; template <int MODE>
; DI void bias_init(f32x16& s0, f32x16& s1, const TP& tp, float fbm, int hi) {
; #pragma unroll
;     for (int r = 0; r < 16; ++r) {
;         const int kvc = 16 * (r >> 3) + (r & 7);
;         if (MODE == 0) { s0[r] = __builtin_fmaf(-L2E, tp.cs[kvc + 8 * hi], fbm); s1[r] = __builtin_fmaf(-L2E, tp.cs[kvc + 32 + 8 * hi], fbm); }
;         else { s0[r] = __builtin_fmaf(tp.sl, (float)kvc, fbm); s1[r] = __builtin_fmaf(tp.sl, (float)(kvc + 32), fbm); }
;     }
; }
; DI float max3_asm(float a, float b, float c) { float r; asm("v_max3_f32 %0, %1, %2, %3" : "=v"(r) : "v"(a), "v"(b), "v"(c)); return r; }
; template <bool MASK>
; DI float mask_rowmax(f32x16& s0, f32x16& s1, const TP& tp) {
;     if (MASK) {
; #pragma unroll
;         for (int r = 0; r < 16; ++r) {
;             const int kvc = 16 * (r >> 3) + (r & 7);
;             const bool v0 = tp.sel && (kvc <= tp.lim) && (kvc > tp.lim2), v1 = tp.sel && (kvc + 32 <= tp.lim) && (kvc + 32 > tp.lim2);
;             s0[r] = v0 ? s0[r] : -1e30f; s1[r] = v1 ? s1[r] : -1e30f;
;         }
;     }
;     const float seed = __builtin_fminf(s0[15], s1[15]);
;     float ma = seed, mb = seed;
; #pragma unroll
;     for (int r = 0; r < 16; r += 2) { ma = max3_asm(ma, s0[r], s1[r]); mb = max3_asm(mb, s0[r + 1], s1[r + 1]); }
;     const float mx = fmaxf(ma, mb);
;     return fmaxf(mx, __shfl_xor(mx, 32));
; }
; template <int MODE, bool MASK, bool WITH_O>
; DI void attn_tile_t(lptr Kt, lptr Vt, const bf16x8 (&qf)[4], f32x16& o0, f32x16& o1, RowState& rs, const TP& tp, int lane) {
;     const int hi = lane >> 5;
;     f32x16 s0, s1;
;     bias_init<MODE>(s0, s1, tp, tp.fb - rs.mref, hi);
;     qk_acc(Kt, qf, s0, s1, lane);
;     const float mx = mask_rowmax<MASK>(s0, s1, tp);
; DI void slc_unit(const Params& P, lptr L, int u, int tid, int lane, int wid) {
;     ...
;     ATT_LOOP_BEGIN(NTS, false, kb_ + (size_t)((int)list[jt] * 64) * PROJ_LD, vb_ + (size_t)((int)list[jt]) * 64, (const float*)nullptr)
;         const int j = (int)list[jt], kv0 = j * 64;
;         const bool sel = (sm[ql * 8 + (j >> 5)] >> (j & 31)) & 1u;
;         if (__any(sel)) {
;             TP tp; tp.cs = nullptr; tp.sl = sl; tp.fb = sl * (float)(kv0 + 8 * hi - t); tp.lim = t - kv0 - 8 * hi; tp.lim2 = -(1 << 30); tp.sel = sel;
;             attn_tile<1>(Kt, Vt, qf, o0, o1, rs, tp, true, lane);
;         }
.LBB0_613:
	v_mov_b32_e32 v0, v253
	s_and_b32 s31, s0, 1
	v_and_b32_e32 v35, 31, v253
	s_waitcnt lgkmcnt(0)
	v_lshrrev_b32_e32 v36, v0, v255
	v_bfe_u32 v34, v255, v35, 1
	v_and_b32_e32 v35, 1, v36
	v_mov_b32_e32 v253, v254
	v_cmp_ne_u32_e32 vcc, 0, v34
	v_cmp_eq_u32_e64 s[28:29], 1, v35
	s_cbranch_vccz .LBB0_618
	s_mul_i32 s33, s31, 0x2400
	v_add_u32_e32 v232, s33, v170
	ds_read_b128 v[102:105], v232 offset:4608
	ds_read_b128 v[106:109], v232
	ds_read_b128 v[110:113], v232 offset:32
	ds_read_b128 v[114:117], v232 offset:4640
	ds_read_b128 v[118:121], v232 offset:64
	ds_read_b128 v[158:161], v232 offset:4672
	ds_read_b128 v[162:165], v232 offset:96
	ds_read_b128 v[166:169], v232 offset:4704
	v_lshl_or_b32 v0, v0, 6, v126
	v_sub_u32_e32 v34, v0, v91
	v_cvt_f32_i32_e32 v34, v34
	s_mov_b32 s0, 2.0
	v_sub_u32_e32 v152, v91, v0
	s_mov_b32 s1, 0x40400000
	v_cmp_lt_i32_e32 vcc, 54, v152
	v_fma_f32 v0, v150, v34, -v101
	s_cmp_eq_u64 vcc, exec
	s_cselect_b64 s[98:99], -1, 0
	s_orn2_b64 s[100:101], s[28:29], s[98:99]
	v_cndmask_b32_e64 v0, v210, v0, s[100:101]
	v_pk_fma_f32 v[36:37], v[94:95], s[0:1], v[0:1] op_sel_hi:[1,1,0]
	s_mov_b32 s0, 4.0
	s_mov_b32 s1, 0x40a00000
	v_pk_fma_f32 v[38:39], v[94:95], s[0:1], v[0:1] op_sel_hi:[1,1,0]
	s_mov_b32 s0, 0x40c00000
	s_mov_b32 s1, 0x40e00000
	v_pk_fma_f32 v[40:41], v[94:95], s[0:1], v[0:1] op_sel_hi:[1,1,0]
	s_mov_b32 s0, 0x41800000
	s_mov_b32 s1, 0x41880000
	v_pk_fma_f32 v[42:43], v[94:95], s[0:1], v[0:1] op_sel_hi:[1,1,0]
	s_mov_b32 s0, 0x41900000
	s_mov_b32 s1, 0x41980000
	v_pk_fma_f32 v[44:45], v[94:95], s[0:1], v[0:1] op_sel_hi:[1,1,0]
	s_mov_b32 s0, 0x41a00000
	s_mov_b32 s1, 0x41a80000
	v_mov_b32_e32 v151, v150
	v_fma_f32 v34, 0, v150, v0
	v_add_f32_e32 v35, v150, v0
	v_pk_fma_f32 v[46:47], v[94:95], s[0:1], v[0:1] op_sel_hi:[1,1,0]
	v_pk_fma_f32 v[48:49], v[94:95], s[18:19], v[0:1] op_sel_hi:[1,1,0]
	v_pk_fma_f32 v[64:65], v[150:151], s[4:5], v[0:1] op_sel_hi:[1,1,0]
	v_pk_fma_f32 v[62:63], v[150:151], s[14:15], v[0:1] op_sel_hi:[1,1,0]
	v_pk_fma_f32 v[60:61], v[150:151], s[16:17], v[0:1] op_sel_hi:[1,1,0]
	v_pk_fma_f32 v[58:59], v[150:151], s[94:95], v[0:1] op_sel_hi:[1,1,0]
	v_pk_fma_f32 v[56:57], v[150:151], s[96:97], v[0:1] op_sel_hi:[1,1,0]
	v_pk_fma_f32 v[54:55], v[150:151], s[84:85], v[0:1] op_sel_hi:[1,1,0]
	v_pk_fma_f32 v[52:53], v[150:151], s[72:73], v[0:1] op_sel_hi:[1,1,0]
	v_pk_fma_f32 v[50:51], v[96:97], s[44:45], v[0:1] op_sel_hi:[1,1,0]
	s_waitcnt lgkmcnt(6)
	v_mfma_f32_32x32x16_bf16 v[34:49], v[106:109], v[66:69], v[34:49]
	v_mfma_f32_32x32x16_bf16 v[50:65], v[102:105], v[66:69], v[50:65]
	s_waitcnt lgkmcnt(5)
	v_mfma_f32_32x32x16_bf16 v[34:49], v[110:113], v[70:73], v[34:49]
	s_waitcnt lgkmcnt(4)
	v_mfma_f32_32x32x16_bf16 v[50:65], v[114:117], v[70:73], v[50:65]
	s_waitcnt lgkmcnt(3)
	v_mfma_f32_32x32x16_bf16 v[34:49], v[118:121], v[74:77], v[34:49]
	s_waitcnt lgkmcnt(2)
	v_mfma_f32_32x32x16_bf16 v[50:65], v[158:161], v[74:77], v[50:65]
	s_waitcnt lgkmcnt(1)
	v_mfma_f32_32x32x16_bf16 v[34:49], v[162:165], v[78:81], v[34:49]
	s_waitcnt lgkmcnt(0)
	v_mfma_f32_32x32x16_bf16 v[50:65], v[166:169], v[78:81], v[50:65]
	s_and_b64 vcc, exec, s[98:99]
	s_cbranch_vccz .Lslc_masked
	s_nop 10
	v_max_f32_e32 v252, v65, v65
	v_max_f32_e32 v228, v49, v49
	v_min_f32_e32 v252, v228, v252
	v_max3_f32 v228, v252, v34, v50
	v_max3_f32 v252, v252, v35, v51
	s_mov_b32 s0, 0xefa18f08
	v_max3_f32 v228, v228, v36, v52
	v_max3_f32 v252, v252, v37, v53
	v_max3_f32 v228, v228, v38, v54
	v_max3_f32 v252, v252, v39, v55
	v_max3_f32 v228, v228, v40, v56
	v_max3_f32 v252, v252, v41, v57
	v_max3_f32 v228, v228, v42, v58
	v_max3_f32 v252, v252, v43, v59
	v_max3_f32 v228, v228, v44, v60
	v_max3_f32 v252, v252, v45, v61
	v_max3_f32 v228, v228, v46, v62
	v_max3_f32 v252, v252, v47, v63
	v_max3_f32 v228, v228, v48, v64
	v_max3_f32 v252, v252, v49, v65
	v_max_f32_e32 v252, v252, v252
	v_max_f32_e32 v228, v228, v228
	v_max_f32_e32 v252, v228, v252
	v_mov_b32_e32 v228, v252
	s_nop 1
	v_permlane32_swap_b32_e32 v228, v252
	s_waitcnt lgkmcnt(0)
	v_max_f32_e32 v252, v252, v228
	v_cmp_lt_f32_e64 s[28:29], s0, v252
	s_mov_b32 s0, 0x41000000
	v_cmp_lt_f32_e32 vcc, s0, v252
	s_mov_b32 s0, 0xc1000000
	v_cmp_gt_f32_e64 s[0:1], s0, v252
	s_and_b64 s[0:1], s[0:1], s[28:29]
	s_andn2_b64 s[0:1], s[0:1], s[22:23]
	s_or_b64 s[0:1], s[0:1], vcc
	s_and_b64 vcc, exec, s[0:1]
	s_cbranch_vccnz .Lsf_rare
; DI unsigned pk_bf16(float lo, float hi) { f32x2 v = {lo, hi}; bf16x2_t b = __builtin_convertvector(v, bf16x2_t); return __builtin_bit_cast(unsigned, b); }
; DI bf16x8 pack8(const f32x16& p, int base) {
;     u32x4 w; w.x = pk_bf16(p[base + 0], p[base + 1]); w.y = pk_bf16(p[base + 2], p[base + 3]); w.z = pk_bf16(p[base + 4], p[base + 5]); w.w = pk_bf16(p[base + 6], p[base + 7]);
;     return __builtin_bit_cast(bf16x8, w);
; template <int MODE, bool MASK, bool WITH_O>
; DI void attn_tile_t(lptr Kt, lptr Vt, const bf16x8 (&qf)[4], f32x16& o0, f32x16& o1, RowState& rs, const TP& tp, int lane) {
;     ...
;     } else {
;         const int i = lane & 31;
;         lptr vp = Vt + i * KPB + hi * 16;
;         float sum = 0.f;
;     ...
;         PV_STEP(s0, 0, 0) PV_STEP(s0, 8, 32) PV_STEP(s1, 0, 64) PV_STEP(s1, 8, 96)
;     ...
;         rs.l += sum;
	v_exp_f32_e32 v252, v34
	v_exp_f32_e32 v103, v35
	v_exp_f32_e32 v111, v36
	v_exp_f32_e32 v105, v37
	v_add_f32_e32 v106, 0, v252
	v_add_f32_e32 v106, v103, v106
	v_add_f32_e32 v104, v111, v106
	v_exp_f32_e32 v106, v38
	v_exp_f32_e32 v107, v39
	v_add_u32_e32 v228, s33, v172
	v_exp_f32_e32 v108, v40
	ds_read_b128 v[236:239], v228 offset:18432
	ds_read_b128 v[240:243], v228 offset:23040
	v_add_f32_e32 v104, v105, v104
	v_exp_f32_e32 v109, v41
	v_add_f32_e32 v104, v106, v104
	v_add_f32_e32 v104, v107, v104
	v_add_f32_e32 v104, v108, v104
	v_add_f32_e32 v110, v109, v104
	v_cvt_pk_bf16_f32 v104, v252, v103
	v_cvt_pk_bf16_f32 v105, v111, v105
	v_cvt_pk_bf16_f32 v106, v106, v107
	v_cvt_pk_bf16_f32 v107, v108, v109
	s_or_b64 s[22:23], s[22:23], s[28:29]
	s_waitcnt lgkmcnt(1)
	v_mfma_f32_32x32x16_bf16 v[18:33], v[236:239], v[104:107], v[18:33]
	s_waitcnt lgkmcnt(0)
	v_mfma_f32_32x32x16_bf16 v[2:17], v[240:243], v[104:107], v[2:17]
	v_exp_f32_e32 v252, v42
	v_exp_f32_e32 v43, v43
	v_exp_f32_e32 v103, v44
	v_exp_f32_e32 v44, v45
	v_add_f32_e32 v229, v252, v110
	v_exp_f32_e32 v45, v46
	v_add_f32_e32 v229, v43, v229
	v_exp_f32_e32 v46, v47
	v_add_f32_e32 v42, v103, v229
	v_exp_f32_e32 v47, v48
	ds_read_b128 v[236:239], v228 offset:18464
	ds_read_b128 v[240:243], v228 offset:23072
	v_add_f32_e32 v42, v44, v42
	v_exp_f32_e32 v48, v49
	v_add_f32_e32 v42, v45, v42
	v_add_f32_e32 v42, v46, v42
	v_add_f32_e32 v42, v47, v42
	v_add_f32_e32 v229, v48, v42
	v_cvt_pk_bf16_f32 v42, v252, v43
	v_cvt_pk_bf16_f32 v43, v103, v44
	v_cvt_pk_bf16_f32 v44, v45, v46
	v_cvt_pk_bf16_f32 v45, v47, v48
	s_waitcnt lgkmcnt(1)
	s_nop 0
	v_mfma_f32_32x32x16_bf16 v[18:33], v[236:239], v[42:45], v[18:33]
	s_waitcnt lgkmcnt(0)
	v_mfma_f32_32x32x16_bf16 v[2:17], v[240:243], v[42:45], v[2:17]
	v_exp_f32_e32 v230, v50
	v_exp_f32_e32 v51, v51
	v_exp_f32_e32 v231, v52
	v_exp_f32_e32 v52, v53
	v_add_f32_e32 v229, v230, v229
	v_exp_f32_e32 v53, v54
	v_add_f32_e32 v229, v51, v229
	v_exp_f32_e32 v54, v55
	v_add_f32_e32 v50, v231, v229
	v_exp_f32_e32 v55, v56
	ds_read_b128 v[42:45], v228 offset:18496
	ds_read_b128 v[46:49], v228 offset:23104
	v_add_f32_e32 v50, v52, v50
	v_exp_f32_e32 v41, v57
	v_add_f32_e32 v50, v53, v50
	v_add_f32_e32 v50, v54, v50
	v_add_f32_e32 v50, v55, v50
	v_add_f32_e32 v56, v41, v50
	v_cvt_pk_bf16_f32 v50, v230, v51
	v_cvt_pk_bf16_f32 v51, v231, v52
	v_cvt_pk_bf16_f32 v52, v53, v54
	v_cvt_pk_bf16_f32 v53, v55, v41
	s_waitcnt lgkmcnt(1)
	s_nop 0
	v_mfma_f32_32x32x16_bf16 v[18:33], v[42:45], v[50:53], v[18:33]
	s_waitcnt lgkmcnt(0)
	v_mfma_f32_32x32x16_bf16 v[2:17], v[46:49], v[50:53], v[2:17]
	v_exp_f32_e32 v38, v58
	v_exp_f32_e32 v34, v59
	v_exp_f32_e32 v0, v60
	v_exp_f32_e32 v35, v61
	v_add_f32_e32 v41, v38, v56
	v_exp_f32_e32 v36, v62
	ds_read_b128 v[42:45], v228 offset:18528
	ds_read_b128 v[46:49], v228 offset:23136
	v_add_f32_e32 v41, v34, v41
	v_exp_f32_e32 v37, v63
	v_exp_f32_e32 v39, v64
	v_exp_f32_e32 v40, v65
	v_add_f32_e32 v41, v0, v41
	v_add_f32_e32 v41, v35, v41
	v_add_f32_e32 v41, v36, v41
	v_add_f32_e32 v41, v37, v41
	v_cvt_pk_bf16_f32 v34, v38, v34
	v_cvt_pk_bf16_f32 v35, v0, v35
	v_cvt_pk_bf16_f32 v36, v36, v37
	v_cvt_pk_bf16_f32 v37, v39, v40
	v_add_f32_e32 v41, v39, v41
	v_add_f32_e32 v41, v40, v41
	s_waitcnt lgkmcnt(1)
	v_mfma_f32_32x32x16_bf16 v[18:33], v[42:45], v[34:37], v[18:33]
	s_waitcnt lgkmcnt(0)
	v_mfma_f32_32x32x16_bf16 v[2:17], v[46:49], v[34:37], v[2:17]
	v_add_f32_e32 v100, v100, v41
	s_branch .LBB0_618

; #define SEAM(k) do { if (IN(k) && IN((k) + 1)) xcd_barrier(xbar_); } while (0)
; #define REP_END(k) if (((PROBE_DBL >> (k)) & 1) && rep_ == 0) grid.sync(); }
; __global__ void __launch_bounds__(512) fwd_kernel(Params P) {
;     ...
;         }
;     REP_END(3) }
;     SEAM(3);
.LBB0_819:
	s_setprio 0
	v_readlane_b32 s36, v251, 22
	v_readlane_b32 s2, v251, 41
	v_readlane_b32 s96, v251, 43
	v_readlane_b32 s37, v251, 23
	v_readlane_b32 s38, v251, 24
	v_readlane_b32 s39, v251, 25
	v_readlane_b32 s3, v251, 42
	v_readlane_b32 s97, v251, 44
	v_readlane_b32 s40, v251, 26
	v_readlane_b32 s41, v251, 27
	v_readlane_b32 s42, v251, 28
	v_readlane_b32 s43, v251, 29
	v_readlane_b32 s44, v251, 30
	v_readlane_b32 s45, v251, 31
	v_readlane_b32 s46, v251, 32
	v_readlane_b32 s47, v251, 33
	v_readlane_b32 s48, v251, 34
	v_readlane_b32 s49, v251, 35
	v_readlane_b32 s50, v251, 36
	v_readlane_b32 s51, v251, 37
